# attention unit epilogue: 8 norm-weight loads hoisted, one wait instead of a vmcnt(0) before each of the 128 stores (on top of previous best)
# speedup vs baseline: 1.0093x; 1.0031x over previous
; __device__ __forceinline__ void dattn_unit(const bf16* __restrict__ Qb, const bf16* __restrict__ Kh, const bf16* __restrict__ Vh, int nq, int kv_lo, int kv_hi, int NT, ...
;     ...
;   if (br == 0 && active) {
;     float ss[16];
; #pragma unroll
;     for (int r = 0; r < 16; ++r) ss[r] = 0.f;
; #pragma unroll
;     for (int d = 0; d < 8; ++d)
; #pragma unroll
;       for (int r = 0; r < 16; ++r) { const float v = o[d][r] * rli[r] - ex[(d * 16 + r) * 64 + lane]; o[d][r] = v; ss[r] = fmaf(v, v, ss[r]); }
.LBB0_953:
	s_cmpk_lt_u32 s21, 0x100
	s_waitcnt lgkmcnt(0)
	s_barrier
	s_cselect_b64 s[0:1], -1, 0
	s_and_b64 s[0:1], s[0:1], s[12:13]
	s_andn2_b64 vcc, exec, s[0:1]
	s_cbranch_vccnz .LBB0_1100
	ds_read2st64_b32 v[130:131], v0 offset1:1
	ds_read2st64_b32 v[134:135], v0 offset0:2 offset1:3
	ds_read2st64_b32 v[146:147], v0 offset0:4 offset1:5
	ds_read2st64_b32 v[152:153], v0 offset0:6 offset1:7
	ds_read2st64_b32 v[166:167], v0 offset0:8 offset1:9
	ds_read2st64_b32 v[148:149], v0 offset0:10 offset1:11
	ds_read2st64_b32 v[180:181], v0 offset0:12 offset1:13
	ds_read2st64_b32 v[178:179], v0 offset0:14 offset1:15
	ds_read2st64_b32 v[132:133], v0 offset0:16 offset1:17
	ds_read2st64_b32 v[136:137], v0 offset0:18 offset1:19
	ds_read2st64_b32 v[168:169], v0 offset0:20 offset1:21
	ds_read2st64_b32 v[176:177], v0 offset0:22 offset1:23
	ds_read2st64_b32 v[188:189], v0 offset0:24 offset1:25
	ds_read2st64_b32 v[190:191], v0 offset0:26 offset1:27
	ds_read2st64_b32 v[184:185], v0 offset0:28 offset1:29
	ds_read2st64_b32 v[182:183], v0 offset0:30 offset1:31
	ds_read2st64_b32 v[156:157], v0 offset0:32 offset1:33
	ds_read2st64_b32 v[170:171], v0 offset0:34 offset1:35
	ds_read2st64_b32 v[192:193], v0 offset0:36 offset1:37
	ds_read2st64_b32 v[194:195], v0 offset0:38 offset1:39
	ds_read2st64_b32 v[196:197], v0 offset0:40 offset1:41
	ds_read2st64_b32 v[198:199], v0 offset0:42 offset1:43
	ds_read2st64_b32 v[200:201], v0 offset0:44 offset1:45
	ds_read2st64_b32 v[186:187], v0 offset0:46 offset1:47
	ds_read2st64_b32 v[162:163], v0 offset0:48 offset1:49
	s_waitcnt lgkmcnt(0)
	v_pk_fma_f32 v[160:161], v[114:115], v[164:165], v[130:131] neg_lo:[0,0,1] neg_hi:[0,0,1]
	v_pk_fma_f32 v[132:133], v[98:99], v[164:165], v[132:133] neg_lo:[0,0,1] neg_hi:[0,0,1]
	v_pk_fma_f32 v[114:115], v[160:161], v[160:161], 0 op_sel_hi:[1,1,0]
	v_pk_fma_f32 v[130:131], v[82:83], v[164:165], v[156:157] neg_lo:[0,0,1] neg_hi:[0,0,1]
	v_pk_fma_f32 v[98:99], v[132:133], v[132:133], v[114:115]
	v_pk_fma_f32 v[114:115], v[66:67], v[164:165], v[162:163] neg_lo:[0,0,1] neg_hi:[0,0,1]
	v_pk_fma_f32 v[82:83], v[130:131], v[130:131], v[98:99]
	ds_read2st64_b32 v[98:99], v0 offset0:50 offset1:51
	ds_read2st64_b32 v[202:203], v0 offset0:52 offset1:53
	ds_read2st64_b32 v[204:205], v0 offset0:54 offset1:55
	v_pk_fma_f32 v[162:163], v[116:117], v[158:159], v[134:135] neg_lo:[0,0,1] neg_hi:[0,0,1]
	v_pk_fma_f32 v[136:137], v[100:101], v[158:159], v[136:137] neg_lo:[0,0,1] neg_hi:[0,0,1]
	v_pk_fma_f32 v[66:67], v[162:163], v[162:163], 0 op_sel_hi:[1,1,0]
	v_pk_fma_f32 v[116:117], v[84:85], v[158:159], v[170:171] neg_lo:[0,0,1] neg_hi:[0,0,1]
	v_pk_fma_f32 v[66:67], v[136:137], v[136:137], v[66:67]
	s_waitcnt lgkmcnt(0)
	v_pk_fma_f32 v[98:99], v[68:69], v[158:159], v[98:99] neg_lo:[0,0,1] neg_hi:[0,0,1]
	v_pk_fma_f32 v[66:67], v[116:117], v[116:117], v[66:67]
	v_pk_fma_f32 v[156:157], v[118:119], v[154:155], v[146:147] neg_lo:[0,0,1] neg_hi:[0,0,1]
	v_pk_fma_f32 v[172:173], v[98:99], v[98:99], v[66:67]
	v_pk_fma_f32 v[66:67], v[156:157], v[156:157], 0 op_sel_hi:[1,1,0]
	v_pk_fma_f32 v[134:135], v[102:103], v[154:155], v[168:169] neg_lo:[0,0,1] neg_hi:[0,0,1]
	v_pk_fma_f32 v[102:103], v[86:87], v[154:155], v[192:193] neg_lo:[0,0,1] neg_hi:[0,0,1]
	v_pk_fma_f32 v[66:67], v[134:135], v[134:135], v[66:67]
	v_pk_fma_f32 v[84:85], v[70:71], v[154:155], v[202:203] neg_lo:[0,0,1] neg_hi:[0,0,1]
	v_pk_fma_f32 v[66:67], v[102:103], v[102:103], v[66:67]
	v_pk_fma_f32 v[152:153], v[120:121], v[150:151], v[152:153] neg_lo:[0,0,1] neg_hi:[0,0,1]
	v_pk_fma_f32 v[170:171], v[84:85], v[84:85], v[66:67]
	v_pk_fma_f32 v[66:67], v[152:153], v[152:153], 0 op_sel_hi:[1,1,0]
	v_pk_fma_f32 v[118:119], v[104:105], v[150:151], v[176:177] neg_lo:[0,0,1] neg_hi:[0,0,1]
	v_pk_fma_f32 v[100:101], v[88:89], v[150:151], v[194:195] neg_lo:[0,0,1] neg_hi:[0,0,1]
	v_pk_fma_f32 v[66:67], v[118:119], v[118:119], v[66:67]
	v_pk_fma_f32 v[174:175], v[114:115], v[114:115], v[82:83]
	v_pk_fma_f32 v[66:67], v[100:101], v[100:101], v[66:67]
	v_pk_fma_f32 v[82:83], v[72:73], v[150:151], v[204:205] neg_lo:[0,0,1] neg_hi:[0,0,1]
	v_pk_fma_f32 v[106:107], v[106:107], v[144:145], v[188:189] neg_lo:[0,0,1] neg_hi:[0,0,1]
	v_pk_fma_f32 v[168:169], v[82:83], v[82:83], v[66:67]
	ds_read2st64_b32 v[66:67], v0 offset0:56 offset1:57
	ds_read2st64_b32 v[70:71], v0 offset0:58 offset1:59
	ds_read2st64_b32 v[72:73], v0 offset0:60 offset1:61
	ds_read2st64_b32 v[188:189], v0 offset0:62 offset1:63
	v_pk_fma_f32 v[148:149], v[124:125], v[142:143], v[148:149] neg_lo:[0,0,1] neg_hi:[0,0,1]
	v_pk_fma_f32 v[146:147], v[122:123], v[144:145], v[166:167] neg_lo:[0,0,1] neg_hi:[0,0,1]
	v_pk_fma_f32 v[120:121], v[108:109], v[142:143], v[190:191] neg_lo:[0,0,1] neg_hi:[0,0,1]
	s_waitcnt lgkmcnt(0)
; __device__ __forceinline__ float xor1(float v) { return dppf<0xB1>(v); }
; __device__ __forceinline__ float xor2(float v) { return dppf<0x4E>(v); }
; __device__ __forceinline__ float xor4s(float v) { return dppf<0x141>(v); }
; __device__ __forceinline__ float xor8(float v) { return dppf<0x128>(v); }
; __device__ __forceinline__ float xor16(float v) { return __builtin_bit_cast(float, __builtin_amdgcn_ds_swizzle(__builtin_bit_cast(int, v), 0x401F)); }
; __device__ __forceinline__ void dattn_unit(const bf16* __restrict__ Qb, const bf16* __restrict__ Kh, const bf16* __restrict__ Vh, int nq, int kv_lo, int kv_hi, int NT, ...
;     ...
;     for (int d = 0; d < 8; ++d)
; #pragma unroll
;       for (int r = 0; r < 16; ++r) { const float v = o[d][r] * rli[r] - ex[(d * 16 + r) * 64 + lane]; o[d][r] = v; ss[r] = fmaf(v, v, ss[r]); }
; #pragma unroll
;     for (int r = 0; r < 16; ++r) { float v = ss[r]; v += xor1(v); v += xor2(v); v += xor4s(v); v += xor8(v); v += xor16(v);
	v_pk_fma_f32 v[88:89], v[74:75], v[144:145], v[66:67] neg_lo:[0,0,1] neg_hi:[0,0,1]
	v_pk_fma_f32 v[66:67], v[148:149], v[148:149], 0 op_sel_hi:[1,1,0]
	v_pk_fma_f32 v[68:69], v[146:147], v[146:147], 0 op_sel_hi:[1,1,0]
	v_pk_fma_f32 v[66:67], v[120:121], v[120:121], v[66:67]
	v_pk_fma_f32 v[104:105], v[92:93], v[142:143], v[198:199] neg_lo:[0,0,1] neg_hi:[0,0,1]
	v_pk_fma_f32 v[68:69], v[106:107], v[106:107], v[68:69]
	v_pk_fma_f32 v[90:91], v[90:91], v[144:145], v[196:197] neg_lo:[0,0,1] neg_hi:[0,0,1]
	v_pk_fma_f32 v[66:67], v[104:105], v[104:105], v[66:67]
	v_pk_fma_f32 v[86:87], v[76:77], v[142:143], v[70:71] neg_lo:[0,0,1] neg_hi:[0,0,1]
	v_pk_fma_f32 v[124:125], v[126:127], v[140:141], v[180:181] neg_lo:[0,0,1] neg_hi:[0,0,1]
	v_pk_fma_f32 v[68:69], v[90:91], v[90:91], v[68:69]
	v_pk_fma_f32 v[166:167], v[86:87], v[86:87], v[66:67]
	v_pk_fma_f32 v[66:67], v[124:125], v[124:125], 0 op_sel_hi:[1,1,0]
	v_pk_fma_f32 v[110:111], v[110:111], v[140:141], v[184:185] neg_lo:[0,0,1] neg_hi:[0,0,1]
	v_pk_fma_f32 v[176:177], v[88:89], v[88:89], v[68:69]
	v_pk_fma_f32 v[66:67], v[110:111], v[110:111], v[66:67]
	v_pk_fma_f32 v[94:95], v[94:95], v[140:141], v[200:201] neg_lo:[0,0,1] neg_hi:[0,0,1]
	v_pk_fma_f32 v[92:93], v[96:97], v[138:139], v[186:187] neg_lo:[0,0,1] neg_hi:[0,0,1]
	ds_read2st64_b32 v[68:69], v0 offset0:64 offset1:65
	ds_read2st64_b32 v[70:71], v0 offset0:66 offset1:67
	ds_read2st64_b32 v[96:97], v0 offset0:68 offset1:69
	v_pk_fma_f32 v[66:67], v[94:95], v[94:95], v[66:67]
	v_pk_fma_f32 v[78:79], v[78:79], v[140:141], v[72:73] neg_lo:[0,0,1] neg_hi:[0,0,1]
	v_pk_fma_f32 v[122:123], v[128:129], v[138:139], v[178:179] neg_lo:[0,0,1] neg_hi:[0,0,1]
	v_pk_fma_f32 v[126:127], v[78:79], v[78:79], v[66:67]
	v_pk_fma_f32 v[66:67], v[122:123], v[122:123], 0 op_sel_hi:[1,1,0]
	v_pk_fma_f32 v[108:109], v[112:113], v[138:139], v[182:183] neg_lo:[0,0,1] neg_hi:[0,0,1]
	v_pk_fma_f32 v[76:77], v[80:81], v[138:139], v[188:189] neg_lo:[0,0,1] neg_hi:[0,0,1]
	v_pk_fma_f32 v[66:67], v[108:109], v[108:109], v[66:67]
	s_waitcnt lgkmcnt(0)
	v_pk_fma_f32 v[74:75], v[50:51], v[164:165], v[68:69] neg_lo:[0,0,1] neg_hi:[0,0,1]
	v_pk_fma_f32 v[66:67], v[92:93], v[92:93], v[66:67]
	v_pk_fma_f32 v[72:73], v[52:53], v[158:159], v[70:71] neg_lo:[0,0,1] neg_hi:[0,0,1]
	v_pk_fma_f32 v[80:81], v[76:77], v[76:77], v[66:67]
	ds_read2st64_b32 v[66:67], v0 offset0:70 offset1:71
	v_pk_fma_f32 v[70:71], v[54:55], v[154:155], v[96:97] neg_lo:[0,0,1] neg_hi:[0,0,1]
	ds_read2st64_b32 v[50:51], v0 offset0:72 offset1:73
	ds_read2st64_b32 v[52:53], v0 offset0:74 offset1:75
	ds_read2st64_b32 v[54:55], v0 offset0:76 offset1:77
	ds_read2st64_b32 v[96:97], v0 offset0:78 offset1:79
	v_pk_fma_f32 v[174:175], v[74:75], v[74:75], v[174:175]
	s_mov_b32 s0, 0x3b800000
	s_waitcnt lgkmcnt(0)
	v_pk_fma_f32 v[68:69], v[56:57], v[150:151], v[66:67] neg_lo:[0,0,1] neg_hi:[0,0,1]
	v_pk_fma_f32 v[66:67], v[58:59], v[144:145], v[50:51] neg_lo:[0,0,1] neg_hi:[0,0,1]
	v_pk_fma_f32 v[56:57], v[60:61], v[142:143], v[52:53] neg_lo:[0,0,1] neg_hi:[0,0,1]
	v_pk_fma_f32 v[52:53], v[62:63], v[140:141], v[54:55] neg_lo:[0,0,1] neg_hi:[0,0,1]
	v_pk_fma_f32 v[50:51], v[64:65], v[138:139], v[96:97] neg_lo:[0,0,1] neg_hi:[0,0,1]
	ds_read2st64_b32 v[54:55], v0 offset0:80 offset1:81
	ds_read2st64_b32 v[58:59], v0 offset0:82 offset1:83
	ds_read2st64_b32 v[60:61], v0 offset0:84 offset1:85
	ds_read2st64_b32 v[112:113], v0 offset0:86 offset1:87
	ds_read2st64_b32 v[190:191], v0 offset0:88 offset1:89
	ds_read2st64_b32 v[62:63], v0 offset0:90 offset1:91
	ds_read2st64_b32 v[96:97], v0 offset0:92 offset1:93
	ds_read2st64_b32 v[64:65], v0 offset0:94 offset1:95
	ds_read2st64_b32 v[128:129], v0 offset0:96 offset1:97
	ds_read2st64_b32 v[192:193], v0 offset0:98 offset1:99
	ds_read2st64_b32 v[194:195], v0 offset0:100 offset1:101
	ds_read2st64_b32 v[196:197], v0 offset0:102 offset1:103
	ds_read2st64_b32 v[178:179], v0 offset0:112 offset1:113
	ds_read2st64_b32 v[198:199], v0 offset0:114 offset1:115
	ds_read2st64_b32 v[200:201], v0 offset0:116 offset1:117
	ds_read2st64_b32 v[202:203], v0 offset0:118 offset1:119
	s_waitcnt lgkmcnt(0)
	v_pk_fma_f32 v[54:55], v[34:35], v[164:165], v[54:55] neg_lo:[0,0,1] neg_hi:[0,0,1]
	v_pk_fma_f32 v[34:35], v[18:19], v[164:165], v[128:129] neg_lo:[0,0,1] neg_hi:[0,0,1]
	v_pk_fma_f32 v[174:175], v[54:55], v[54:55], v[174:175]
	v_pk_fma_f32 v[2:3], v[2:3], v[164:165], v[178:179] neg_lo:[0,0,1] neg_hi:[0,0,1]
	v_pk_fma_f32 v[18:19], v[34:35], v[34:35], v[174:175]
	ds_read2st64_b32 v[204:205], v0 offset0:104 offset1:105
	ds_read2st64_b32 v[186:187], v0 offset0:106 offset1:107
	ds_read2st64_b32 v[182:183], v0 offset0:108 offset1:109
	ds_read2st64_b32 v[178:179], v0 offset0:110 offset1:111
	v_pk_fma_f32 v[18:19], v[2:3], v[2:3], v[18:19]
	v_pk_fma_f32 v[58:59], v[36:37], v[158:159], v[58:59] neg_lo:[0,0,1] neg_hi:[0,0,1]
	v_pk_fma_f32 v[36:37], v[20:21], v[158:159], v[192:193] neg_lo:[0,0,1] neg_hi:[0,0,1]
	v_mov_b32_dpp v128, v18 quad_perm:[1,0,3,2] row_mask:0xf bank_mask:0xf bound_ctrl:1
	v_mov_b32_dpp v129, v19 quad_perm:[1,0,3,2] row_mask:0xf bank_mask:0xf bound_ctrl:1
	v_pk_add_f32 v[18:19], v[18:19], v[128:129]
	v_pk_fma_f32 v[4:5], v[4:5], v[158:159], v[198:199] neg_lo:[0,0,1] neg_hi:[0,0,1]
	v_pk_fma_f32 v[60:61], v[38:39], v[154:155], v[60:61] neg_lo:[0,0,1] neg_hi:[0,0,1]
	v_mov_b32_dpp v128, v18 quad_perm:[2,3,0,1] row_mask:0xf bank_mask:0xf bound_ctrl:1
	v_mov_b32_dpp v129, v19 quad_perm:[2,3,0,1] row_mask:0xf bank_mask:0xf bound_ctrl:1
	v_pk_add_f32 v[18:19], v[18:19], v[128:129]
	v_pk_fma_f32 v[22:23], v[22:23], v[154:155], v[194:195] neg_lo:[0,0,1] neg_hi:[0,0,1]
	v_pk_fma_f32 v[6:7], v[6:7], v[154:155], v[200:201] neg_lo:[0,0,1] neg_hi:[0,0,1]
	v_mov_b32_dpp v128, v18 row_half_mirror row_mask:0xf bank_mask:0xf bound_ctrl:1
	v_mov_b32_dpp v129, v19 row_half_mirror row_mask:0xf bank_mask:0xf bound_ctrl:1
	v_pk_add_f32 v[18:19], v[18:19], v[128:129]
	v_pk_fma_f32 v[40:41], v[40:41], v[150:151], v[112:113] neg_lo:[0,0,1] neg_hi:[0,0,1]
	v_pk_fma_f32 v[24:25], v[24:25], v[150:151], v[196:197] neg_lo:[0,0,1] neg_hi:[0,0,1]
	v_mov_b32_dpp v128, v18 row_ror:8 row_mask:0xf bank_mask:0xf bound_ctrl:1
	v_mov_b32_dpp v129, v19 row_ror:8 row_mask:0xf bank_mask:0xf bound_ctrl:1
	v_pk_add_f32 v[18:19], v[18:19], v[128:129]
	ds_swizzle_b32 v128, v18 offset:swizzle(SWAP,16)
	ds_swizzle_b32 v129, v19 offset:swizzle(SWAP,16)
	v_pk_fma_f32 v[8:9], v[8:9], v[150:151], v[202:203] neg_lo:[0,0,1] neg_hi:[0,0,1]
	v_pk_fma_f32 v[42:43], v[42:43], v[144:145], v[190:191] neg_lo:[0,0,1] neg_hi:[0,0,1]
	s_waitcnt lgkmcnt(0)
; __device__ __forceinline__ float xor1(float v) { return dppf<0xB1>(v); }
; __device__ __forceinline__ float xor2(float v) { return dppf<0x4E>(v); }
; __device__ __forceinline__ float xor4s(float v) { return dppf<0x141>(v); }
; __device__ __forceinline__ float xor8(float v) { return dppf<0x128>(v); }
; __device__ __forceinline__ float xor16(float v) { return __builtin_bit_cast(float, __builtin_amdgcn_ds_swizzle(__builtin_bit_cast(int, v), 0x401F)); }
; __device__ __forceinline__ void dattn_unit(const bf16* __restrict__ Qb, const bf16* __restrict__ Kh, const bf16* __restrict__ Vh, int nq, int kv_lo, int kv_hi, int NT, ...
;     ...
;       for (int r = 0; r < 16; ++r) { const float v = o[d][r] * rli[r] - ex[(d * 16 + r) * 64 + lane]; o[d][r] = v; ss[r] = fmaf(v, v, ss[r]); }
; #pragma unroll
;     for (int r = 0; r < 16; ++r) { float v = ss[r]; v += xor1(v); v += xor2(v); v += xor4s(v); v += xor8(v); v += xor16(v);
;         ss[r] = rsqrtf(v * (1.f / 256.f) + LN_EPS) * (1.f - LAM_INIT); }
; #pragma unroll
;     for (int d = 0; d < 8; ++d) { const float g = gnorm[32 * d + r32];
	v_pk_fma_f32 v[26:27], v[26:27], v[144:145], v[204:205] neg_lo:[0,0,1] neg_hi:[0,0,1]
	v_pk_fma_f32 v[62:63], v[44:45], v[142:143], v[62:63] neg_lo:[0,0,1] neg_hi:[0,0,1]
	v_pk_add_f32 v[18:19], v[18:19], v[128:129]
	v_pk_fma_f32 v[128:129], v[72:73], v[72:73], v[172:173]
	v_pk_fma_f32 v[164:165], v[18:19], s[0:1], v[210:211] op_sel_hi:[1,0,0]
	v_pk_fma_f32 v[128:129], v[58:59], v[58:59], v[128:129]
	v_mul_f32_e32 v18, 0x4b800000, v164
	v_cmp_gt_f32_e32 vcc, s92, v164
	v_pk_fma_f32 v[20:21], v[36:37], v[36:37], v[128:129]
	v_pk_fma_f32 v[46:47], v[46:47], v[140:141], v[96:97] neg_lo:[0,0,1] neg_hi:[0,0,1]
	v_cndmask_b32_e32 v18, v164, v18, vcc
	v_rsq_f32_e32 v206, v18
	ds_read2st64_b32 v[18:19], v0 offset0:120 offset1:121
	ds_read2st64_b32 v[188:189], v0 offset0:122 offset1:123
	ds_read2st64_b32 v[184:185], v0 offset0:124 offset1:125
	ds_read2st64_b32 v[180:181], v0 offset0:126 offset1:127
	v_lshlrev_b32_e32 v0, 1, v230
	v_lshl_or_b32 v0, v231, 15, v0
	s_waitcnt lgkmcnt(0)
	v_pk_fma_f32 v[10:11], v[10:11], v[144:145], v[18:19] neg_lo:[0,0,1] neg_hi:[0,0,1]
	v_lshl_add_u64 v[18:19], s[10:11], 0, v[0:1]
	v_readlane_b32 s4, v253, 16
	v_lshlrev_b32_e32 v0, 2, v230
	v_readlane_b32 s12, v253, 24
	v_readlane_b32 s13, v253, 25
	v_pk_fma_f32 v[20:21], v[4:5], v[4:5], v[20:21]
	v_pk_fma_f32 v[30:31], v[30:31], v[140:141], v[182:183] neg_lo:[0,0,1] neg_hi:[0,0,1]
	v_pk_fma_f32 v[14:15], v[14:15], v[140:141], v[184:185] neg_lo:[0,0,1] neg_hi:[0,0,1]
	v_mov_b32_dpp v128, v20 quad_perm:[1,0,3,2] row_mask:0xf bank_mask:0xf bound_ctrl:1
	v_mov_b32_dpp v129, v21 quad_perm:[1,0,3,2] row_mask:0xf bank_mask:0xf bound_ctrl:1
	global_load_dword v164, v0, s[12:13]
	global_load_dword v240, v0, s[12:13] offset:128
	global_load_dword v241, v0, s[12:13] offset:256
	global_load_dword v242, v0, s[12:13] offset:384
	global_load_dword v243, v0, s[12:13] offset:512
	global_load_dword v244, v0, s[12:13] offset:640
	global_load_dword v245, v0, s[12:13] offset:768
	global_load_dword v246, v0, s[12:13] offset:896
	v_pk_add_f32 v[20:21], v[20:21], v[128:129]
	v_pk_fma_f32 v[44:45], v[48:49], v[138:139], v[64:65] neg_lo:[0,0,1] neg_hi:[0,0,1]
	v_mul_f32_e32 v207, 0x45800000, v206
	v_mov_b32_dpp v128, v20 quad_perm:[2,3,0,1] row_mask:0xf bank_mask:0xf bound_ctrl:1
	v_mov_b32_dpp v129, v21 quad_perm:[2,3,0,1] row_mask:0xf bank_mask:0xf bound_ctrl:1
	v_pk_add_f32 v[20:21], v[20:21], v[128:129]
	v_cndmask_b32_e32 v48, v206, v207, vcc
	v_cmp_gt_f32_e64 s[0:1], s92, v165
	v_mov_b32_dpp v128, v20 row_half_mirror row_mask:0xf bank_mask:0xf bound_ctrl:1
	v_mov_b32_dpp v129, v21 row_half_mirror row_mask:0xf bank_mask:0xf bound_ctrl:1
	v_pk_add_f32 v[20:21], v[20:21], v[128:129]
	v_readlane_b32 s5, v253, 17
	v_mul_f32_e32 v64, 0x3f4ccccd, v48
	v_mov_b32_dpp v128, v20 row_ror:8 row_mask:0xf bank_mask:0xf bound_ctrl:1
	v_mov_b32_dpp v129, v21 row_ror:8 row_mask:0xf bank_mask:0xf bound_ctrl:1
	v_pk_add_f32 v[172:173], v[20:21], v[128:129]
	v_pk_fma_f32 v[20:21], v[70:71], v[70:71], v[170:171]
	ds_swizzle_b32 v174, v172 offset:swizzle(SWAP,16)
	v_pk_fma_f32 v[20:21], v[60:61], v[60:61], v[20:21]
	ds_swizzle_b32 v175, v173 offset:swizzle(SWAP,16)
	v_pk_fma_f32 v[20:21], v[22:23], v[22:23], v[20:21]
	v_readlane_b32 s6, v253, 18
	v_pk_fma_f32 v[20:21], v[6:7], v[6:7], v[20:21]
	v_readlane_b32 s7, v253, 19
	v_readlane_b32 s8, v253, 20
	v_mov_b32_dpp v38, v20 quad_perm:[1,0,3,2] row_mask:0xf bank_mask:0xf bound_ctrl:1
	v_mov_b32_dpp v39, v21 quad_perm:[1,0,3,2] row_mask:0xf bank_mask:0xf bound_ctrl:1
	v_pk_add_f32 v[20:21], v[20:21], v[38:39]
	v_readlane_b32 s9, v253, 21
	v_readlane_b32 s10, v253, 22
	v_mov_b32_dpp v38, v20 quad_perm:[2,3,0,1] row_mask:0xf bank_mask:0xf bound_ctrl:1
	v_mov_b32_dpp v39, v21 quad_perm:[2,3,0,1] row_mask:0xf bank_mask:0xf bound_ctrl:1
	v_pk_add_f32 v[20:21], v[20:21], v[38:39]
	v_readlane_b32 s11, v253, 23
	v_readlane_b32 s14, v253, 26
	v_mov_b32_dpp v38, v20 row_half_mirror row_mask:0xf bank_mask:0xf bound_ctrl:1
	v_mov_b32_dpp v39, v21 row_half_mirror row_mask:0xf bank_mask:0xf bound_ctrl:1
	v_pk_add_f32 v[20:21], v[20:21], v[38:39]
	v_readlane_b32 s15, v253, 27
	v_readlane_b32 s16, v253, 28
	v_mov_b32_dpp v38, v20 row_ror:8 row_mask:0xf bank_mask:0xf bound_ctrl:1
	v_mov_b32_dpp v39, v21 row_ror:8 row_mask:0xf bank_mask:0xf bound_ctrl:1
	v_pk_add_f32 v[154:155], v[20:21], v[38:39]
	v_pk_fma_f32 v[20:21], v[68:69], v[68:69], v[168:169]
	ds_swizzle_b32 v158, v154 offset:swizzle(SWAP,16)
	v_pk_fma_f32 v[20:21], v[40:41], v[40:41], v[20:21]
	ds_swizzle_b32 v159, v155 offset:swizzle(SWAP,16)
	v_pk_fma_f32 v[20:21], v[24:25], v[24:25], v[20:21]
	v_readlane_b32 s17, v253, 29
	v_pk_fma_f32 v[20:21], v[8:9], v[8:9], v[20:21]
	v_readlane_b32 s18, v253, 30
	v_readlane_b32 s19, v253, 31
	v_mov_b32_dpp v38, v20 quad_perm:[1,0,3,2] row_mask:0xf bank_mask:0xf bound_ctrl:1
	v_mov_b32_dpp v39, v21 quad_perm:[1,0,3,2] row_mask:0xf bank_mask:0xf bound_ctrl:1
	v_pk_add_f32 v[20:21], v[20:21], v[38:39]
	s_nop 1
	v_mov_b32_dpp v38, v20 quad_perm:[2,3,0,1] row_mask:0xf bank_mask:0xf bound_ctrl:1
	v_mov_b32_dpp v39, v21 quad_perm:[2,3,0,1] row_mask:0xf bank_mask:0xf bound_ctrl:1
	v_pk_add_f32 v[20:21], v[20:21], v[38:39]
	s_nop 1
	v_mov_b32_dpp v38, v20 row_half_mirror row_mask:0xf bank_mask:0xf bound_ctrl:1
	v_mov_b32_dpp v39, v21 row_half_mirror row_mask:0xf bank_mask:0xf bound_ctrl:1
	v_pk_add_f32 v[20:21], v[20:21], v[38:39]
	s_nop 1
	v_mov_b32_dpp v38, v20 row_ror:8 row_mask:0xf bank_mask:0xf bound_ctrl:1
	v_mov_b32_dpp v39, v21 row_ror:8 row_mask:0xf bank_mask:0xf bound_ctrl:1
	v_pk_add_f32 v[112:113], v[20:21], v[38:39]
	v_pk_fma_f32 v[20:21], v[66:67], v[66:67], v[176:177]
; __device__ __forceinline__ unsigned f2bf(float f) { unsigned u = __builtin_bit_cast(unsigned, f); return (u + 0x7fffu + ((u >> 16) & 1u)) >> 16; }
; __device__ __forceinline__ float xor1(float v) { return dppf<0xB1>(v); }
; __device__ __forceinline__ float xor2(float v) { return dppf<0x4E>(v); }
; __device__ __forceinline__ float xor4s(float v) { return dppf<0x141>(v); }
; __device__ __forceinline__ float xor8(float v) { return dppf<0x128>(v); }
; __device__ __forceinline__ float xor16(float v) { return __builtin_bit_cast(float, __builtin_amdgcn_ds_swizzle(__builtin_bit_cast(int, v), 0x401F)); }
; __device__ __forceinline__ void dattn_unit(const bf16* __restrict__ Qb, const bf16* __restrict__ Kh, const bf16* __restrict__ Vh, int nq, int kv_lo, int kv_hi, int NT, ...
;     ...
;     for (int r = 0; r < 16; ++r) { float v = ss[r]; v += xor1(v); v += xor2(v); v += xor4s(v); v += xor8(v); v += xor16(v);
;         ss[r] = rsqrtf(v * (1.f / 256.f) + LN_EPS) * (1.f - LAM_INIT); }
; #pragma unroll
;     for (int d = 0; d < 8; ++d) { const float g = gnorm[32 * d + r32];
; #pragma unroll
;       for (int r = 0; r < 16; ++r) { const int rk = rg * 32 + (r & 3) + 8 * (r >> 2);
;           if (rk + 4 * hi < nq) *(unsigned short*)((unsigned char*)outp + (size_t)rk * 8192 + 64 * d + (unsigned)(hi * (4 * 8192) + r32 * 2)) = (unsigned short)f2bf(o[d][r] * ss[r] * g); } }
	ds_swizzle_b32 v128, v112 offset:swizzle(SWAP,16)
	v_pk_fma_f32 v[20:21], v[42:43], v[42:43], v[20:21]
	ds_swizzle_b32 v129, v113 offset:swizzle(SWAP,16)
	v_pk_fma_f32 v[20:21], v[26:27], v[26:27], v[20:21]
	s_nop 0
	v_pk_fma_f32 v[20:21], v[10:11], v[10:11], v[20:21]
	s_nop 1
	v_mov_b32_dpp v38, v20 quad_perm:[1,0,3,2] row_mask:0xf bank_mask:0xf bound_ctrl:1
	v_mov_b32_dpp v39, v21 quad_perm:[1,0,3,2] row_mask:0xf bank_mask:0xf bound_ctrl:1
	v_pk_add_f32 v[20:21], v[20:21], v[38:39]
	s_nop 1
	v_mov_b32_dpp v38, v20 quad_perm:[2,3,0,1] row_mask:0xf bank_mask:0xf bound_ctrl:1
	v_mov_b32_dpp v39, v21 quad_perm:[2,3,0,1] row_mask:0xf bank_mask:0xf bound_ctrl:1
	v_pk_add_f32 v[20:21], v[20:21], v[38:39]
	s_nop 1
	v_mov_b32_dpp v38, v20 row_half_mirror row_mask:0xf bank_mask:0xf bound_ctrl:1
	v_mov_b32_dpp v39, v21 row_half_mirror row_mask:0xf bank_mask:0xf bound_ctrl:1
	v_pk_add_f32 v[20:21], v[20:21], v[38:39]
	s_nop 1
	v_mov_b32_dpp v38, v20 row_ror:8 row_mask:0xf bank_mask:0xf bound_ctrl:1
	v_mov_b32_dpp v39, v21 row_ror:8 row_mask:0xf bank_mask:0xf bound_ctrl:1
	v_pk_add_f32 v[150:151], v[20:21], v[38:39]
	v_pk_fma_f32 v[20:21], v[56:57], v[56:57], v[166:167]
	v_pk_fma_f32 v[38:39], v[28:29], v[142:143], v[186:187] neg_lo:[0,0,1] neg_hi:[0,0,1]
	v_pk_fma_f32 v[20:21], v[62:63], v[62:63], v[20:21]
	ds_swizzle_b32 v168, v150 offset:swizzle(SWAP,16)
	v_pk_fma_f32 v[28:29], v[38:39], v[38:39], v[20:21]
	v_pk_fma_f32 v[20:21], v[12:13], v[142:143], v[188:189] neg_lo:[0,0,1] neg_hi:[0,0,1]
	ds_swizzle_b32 v169, v151 offset:swizzle(SWAP,16)
	v_pk_fma_f32 v[12:13], v[20:21], v[20:21], v[28:29]
	v_sub_u32_e32 v166, s20, v232
	v_cmp_lt_u32_e32 vcc, s80, v166
	v_mov_b32_dpp v28, v12 quad_perm:[1,0,3,2] row_mask:0xf bank_mask:0xf bound_ctrl:1
	v_mov_b32_dpp v29, v13 quad_perm:[1,0,3,2] row_mask:0xf bank_mask:0xf bound_ctrl:1
	v_pk_add_f32 v[12:13], v[12:13], v[28:29]
	s_nop 1
	v_mov_b32_dpp v28, v12 quad_perm:[2,3,0,1] row_mask:0xf bank_mask:0xf bound_ctrl:1
	v_mov_b32_dpp v29, v13 quad_perm:[2,3,0,1] row_mask:0xf bank_mask:0xf bound_ctrl:1
	v_pk_add_f32 v[12:13], v[12:13], v[28:29]
	s_nop 1
	v_mov_b32_dpp v28, v12 row_half_mirror row_mask:0xf bank_mask:0xf bound_ctrl:1
	v_mov_b32_dpp v29, v13 row_half_mirror row_mask:0xf bank_mask:0xf bound_ctrl:1
	v_pk_add_f32 v[12:13], v[12:13], v[28:29]
	s_nop 1
	v_mov_b32_dpp v28, v12 row_ror:8 row_mask:0xf bank_mask:0xf bound_ctrl:1
	v_mov_b32_dpp v29, v13 row_ror:8 row_mask:0xf bank_mask:0xf bound_ctrl:1
	v_pk_add_f32 v[142:143], v[12:13], v[28:29]
	v_pk_fma_f32 v[12:13], v[52:53], v[52:53], v[126:127]
	ds_swizzle_b32 v144, v142 offset:swizzle(SWAP,16)
	v_pk_fma_f32 v[12:13], v[46:47], v[46:47], v[12:13]
	ds_swizzle_b32 v145, v143 offset:swizzle(SWAP,16)
	v_pk_fma_f32 v[12:13], v[30:31], v[30:31], v[12:13]
	s_nop 0
	v_pk_fma_f32 v[12:13], v[14:15], v[14:15], v[12:13]
	s_nop 1
	v_mov_b32_dpp v28, v12 quad_perm:[1,0,3,2] row_mask:0xf bank_mask:0xf bound_ctrl:1
	v_mov_b32_dpp v29, v13 quad_perm:[1,0,3,2] row_mask:0xf bank_mask:0xf bound_ctrl:1
	v_pk_add_f32 v[12:13], v[12:13], v[28:29]
	s_nop 1
	v_mov_b32_dpp v28, v12 quad_perm:[2,3,0,1] row_mask:0xf bank_mask:0xf bound_ctrl:1
	v_mov_b32_dpp v29, v13 quad_perm:[2,3,0,1] row_mask:0xf bank_mask:0xf bound_ctrl:1
	v_pk_add_f32 v[12:13], v[12:13], v[28:29]
	s_nop 1
	v_mov_b32_dpp v28, v12 row_half_mirror row_mask:0xf bank_mask:0xf bound_ctrl:1
	v_mov_b32_dpp v29, v13 row_half_mirror row_mask:0xf bank_mask:0xf bound_ctrl:1
	v_pk_add_f32 v[12:13], v[12:13], v[28:29]
	s_nop 1
	v_mov_b32_dpp v28, v12 row_ror:8 row_mask:0xf bank_mask:0xf bound_ctrl:1
	v_mov_b32_dpp v29, v13 row_ror:8 row_mask:0xf bank_mask:0xf bound_ctrl:1
	v_pk_add_f32 v[96:97], v[12:13], v[28:29]
	v_pk_fma_f32 v[12:13], v[50:51], v[50:51], v[80:81]
	v_pk_fma_f32 v[28:29], v[32:33], v[138:139], v[178:179] neg_lo:[0,0,1] neg_hi:[0,0,1]
	v_pk_fma_f32 v[12:13], v[44:45], v[44:45], v[12:13]
	ds_swizzle_b32 v126, v96 offset:swizzle(SWAP,16)
	v_pk_fma_f32 v[32:33], v[28:29], v[28:29], v[12:13]
	v_pk_fma_f32 v[12:13], v[16:17], v[138:139], v[180:181] neg_lo:[0,0,1] neg_hi:[0,0,1]
	ds_swizzle_b32 v127, v97 offset:swizzle(SWAP,16)
	v_pk_fma_f32 v[16:17], v[12:13], v[12:13], v[32:33]
	s_nop 1
	v_mov_b32_dpp v32, v16 quad_perm:[1,0,3,2] row_mask:0xf bank_mask:0xf bound_ctrl:1
	v_mov_b32_dpp v33, v17 quad_perm:[1,0,3,2] row_mask:0xf bank_mask:0xf bound_ctrl:1
	v_pk_add_f32 v[16:17], v[16:17], v[32:33]
	s_nop 1
	v_mov_b32_dpp v32, v16 quad_perm:[2,3,0,1] row_mask:0xf bank_mask:0xf bound_ctrl:1
	v_mov_b32_dpp v33, v17 quad_perm:[2,3,0,1] row_mask:0xf bank_mask:0xf bound_ctrl:1
	v_pk_add_f32 v[16:17], v[16:17], v[32:33]
	s_nop 1
	v_mov_b32_dpp v32, v16 row_half_mirror row_mask:0xf bank_mask:0xf bound_ctrl:1
	v_mov_b32_dpp v33, v17 row_half_mirror row_mask:0xf bank_mask:0xf bound_ctrl:1
	v_pk_add_f32 v[16:17], v[16:17], v[32:33]
	s_nop 1
	v_mov_b32_dpp v32, v16 row_ror:8 row_mask:0xf bank_mask:0xf bound_ctrl:1
	v_mov_b32_dpp v33, v17 row_ror:8 row_mask:0xf bank_mask:0xf bound_ctrl:1
	v_pk_add_f32 v[16:17], v[16:17], v[32:33]
	ds_swizzle_b32 v32, v16 offset:swizzle(SWAP,16)
	ds_swizzle_b32 v33, v17 offset:swizzle(SWAP,16)
	s_waitcnt vmcnt(0)
	s_and_saveexec_b64 s[4:5], vcc
	s_cbranch_execz .LBB0_956
	v_mul_f32_e32 v48, v160, v64
	v_mul_f32_e32 v48, v48, v164
	v_bfe_u32 v49, v48, 16, 1
	s_lshl_b32 s46, s83, 18
	v_add3_u32 v65, v48, v49, s42
	v_lshl_add_u64 v[48:49], v[18:19], 0, s[46:47]
	global_store_short_d16_hi v[48:49], v65, off
; __device__ __forceinline__ unsigned f2bf(float f) { unsigned u = __builtin_bit_cast(unsigned, f); return (u + 0x7fffu + ((u >> 16) & 1u)) >> 16; }
; __device__ __forceinline__ void dattn_unit(const bf16* __restrict__ Qb, const bf16* __restrict__ Kh, const bf16* __restrict__ Vh, int nq, int kv_lo, int kv_hi, int NT, ...
;     ...
;     for (int d = 0; d < 8; ++d) { const float g = gnorm[32 * d + r32];
; #pragma unroll
;       for (int r = 0; r < 16; ++r) { const int rk = rg * 32 + (r & 3) + 8 * (r >> 2);
;           if (rk + 4 * hi < nq) *(unsigned short*)((unsigned char*)outp + (size_t)rk * 8192 + 64 * d + (unsigned)(hi * (4 * 8192) + r32 * 2)) = (unsigned short)f2bf(o[d][r] * ss[r] * g); } }
.LBB0_956:
	s_or_b64 exec, exec, s[4:5]
	v_mul_f32_e32 v48, 0x4b800000, v165
	v_cndmask_b32_e64 v48, v165, v48, s[0:1]
	v_rsq_f32_e32 v48, v48
	s_or_b32 s81, s80, 1
	v_mul_f32_e32 v49, 0x45800000, v48
	v_cndmask_b32_e64 v48, v48, v49, s[0:1]
	v_mul_f32_e32 v65, 0x3f4ccccd, v48
	v_cmp_lt_u32_e64 s[0:1], s81, v166
	s_and_saveexec_b64 s[4:5], s[0:1]
	s_cbranch_execz .LBB0_958
	v_mul_f32_e32 v48, v161, v65
	v_mul_f32_e32 v48, v48, v164
	v_bfe_u32 v49, v48, 16, 1
	s_lshl_b32 s46, s81, 13
	v_add3_u32 v80, v48, v49, s42
	v_lshl_add_u64 v[48:49], v[18:19], 0, s[46:47]
	global_store_short_d16_hi v[48:49], v80, off
.LBB0_958:
	s_or_b64 exec, exec, s[4:5]
	s_waitcnt lgkmcnt(0)
	v_pk_add_f32 v[48:49], v[172:173], v[174:175]
	s_mov_b32 s2, 0x3b800000
	v_pk_fma_f32 v[48:49], v[48:49], s[2:3], v[210:211] op_sel_hi:[1,0,0]
	s_or_b32 s44, s80, 2
	v_mul_f32_e32 v80, 0x4b800000, v48
	v_cmp_gt_f32_e64 s[4:5], s92, v48
	v_cmp_gt_f32_e64 s[6:7], s92, v49
	s_nop 0
	v_cndmask_b32_e64 v48, v48, v80, s[4:5]
	v_rsq_f32_e32 v48, v48
	s_nop 0
	v_mul_f32_e32 v80, 0x45800000, v48
	v_cndmask_b32_e64 v48, v48, v80, s[4:5]
	v_mul_f32_e32 v80, 0x3f4ccccd, v48
	v_cmp_lt_u32_e64 s[4:5], s44, v166
	s_and_saveexec_b64 s[8:9], s[4:5]
	s_cbranch_execz .LBB0_960
	v_mul_f32_e32 v48, v162, v80
	v_mul_f32_e32 v48, v48, v164
	v_bfe_u32 v81, v48, 16, 1
	s_lshl_b32 s46, s44, 13
	v_add3_u32 v48, v48, v81, s42
	v_lshl_add_u64 v[138:139], v[18:19], 0, s[46:47]
	global_store_short_d16_hi v[138:139], v48, off
.LBB0_960:
	s_or_b64 exec, exec, s[8:9]
	v_mul_f32_e32 v48, 0x4b800000, v49
	v_cndmask_b32_e64 v48, v49, v48, s[6:7]
	v_rsq_f32_e32 v48, v48
	s_or_b32 s93, s80, 3
	v_mul_f32_e32 v49, 0x45800000, v48
	v_cndmask_b32_e64 v48, v48, v49, s[6:7]
	v_mul_f32_e32 v81, 0x3f4ccccd, v48
	v_cmp_lt_u32_e64 s[6:7], s93, v166
	s_and_saveexec_b64 s[8:9], s[6:7]
	s_cbranch_execz .LBB0_962
	v_mul_f32_e32 v48, v163, v81
	v_mul_f32_e32 v48, v48, v164
	v_bfe_u32 v49, v48, 16, 1
	s_lshl_b32 s46, s93, 13
	v_add3_u32 v138, v48, v49, s42
	v_lshl_add_u64 v[48:49], v[18:19], 0, s[46:47]
	global_store_short_d16_hi v[48:49], v138, off
.LBB0_962:
	s_or_b64 exec, exec, s[8:9]
	v_pk_add_f32 v[48:49], v[154:155], v[158:159]
	s_or_b32 s50, s80, 8
	v_pk_fma_f32 v[48:49], v[48:49], s[2:3], v[210:211] op_sel_hi:[1,0,0]
	s_nop 0
	v_mul_f32_e32 v138, 0x4b800000, v48
	v_cmp_gt_f32_e64 s[8:9], s92, v48
	v_cmp_gt_f32_e64 s[10:11], s92, v49
	s_nop 0
	v_cndmask_b32_e64 v48, v48, v138, s[8:9]
	v_rsq_f32_e32 v48, v48
	s_nop 0
	v_mul_f32_e32 v138, 0x45800000, v48
	v_cndmask_b32_e64 v48, v48, v138, s[8:9]
	v_mul_f32_e32 v138, 0x3f4ccccd, v48
	v_cmp_lt_u32_e64 s[8:9], s50, v166
	s_and_saveexec_b64 s[12:13], s[8:9]
	s_cbranch_execz .LBB0_964
	v_mul_f32_e32 v48, v156, v138
	v_mul_f32_e32 v48, v48, v164
	v_bfe_u32 v139, v48, 16, 1
	s_lshl_b32 s46, s50, 13
	v_add3_u32 v48, v48, v139, s42
	v_lshl_add_u64 v[140:141], v[18:19], 0, s[46:47]
	global_store_short_d16_hi v[140:141], v48, off
.LBB0_964:
	s_or_b64 exec, exec, s[12:13]
	v_mul_f32_e32 v48, 0x4b800000, v49
	v_cndmask_b32_e64 v48, v49, v48, s[10:11]
	v_rsq_f32_e32 v48, v48
	s_or_b32 s58, s80, 9
	v_mul_f32_e32 v49, 0x45800000, v48
	v_cndmask_b32_e64 v48, v48, v49, s[10:11]
	v_mul_f32_e32 v139, 0x3f4ccccd, v48
	v_cmp_lt_u32_e64 s[10:11], s58, v166
	s_and_saveexec_b64 s[12:13], s[10:11]
	s_cbranch_execz .LBB0_966
	v_mul_f32_e32 v48, v157, v139
	v_mul_f32_e32 v48, v48, v164
	v_bfe_u32 v49, v48, 16, 1
	s_lshl_b32 s46, s58, 13
	v_add3_u32 v140, v48, v49, s42
	v_lshl_add_u64 v[48:49], v[18:19], 0, s[46:47]
	global_store_short_d16_hi v[48:49], v140, off
.LBB0_966:
	s_or_b64 exec, exec, s[12:13]
	v_pk_add_f32 v[48:49], v[112:113], v[128:129]
	s_or_b32 s45, s80, 10
	v_pk_fma_f32 v[48:49], v[48:49], s[2:3], v[210:211] op_sel_hi:[1,0,0]
	s_nop 0
	v_mul_f32_e32 v112, 0x4b800000, v48
	v_cmp_gt_f32_e64 s[12:13], s92, v48
	v_cmp_gt_f32_e64 s[14:15], s92, v49
	s_nop 0
	v_cndmask_b32_e64 v48, v48, v112, s[12:13]
	v_rsq_f32_e32 v48, v48
	s_nop 0
	v_mul_f32_e32 v112, 0x45800000, v48
	v_cndmask_b32_e64 v48, v48, v112, s[12:13]
	v_mul_f32_e32 v112, 0x3f4ccccd, v48
	v_cmp_lt_u32_e64 s[12:13], s45, v166
	s_and_saveexec_b64 s[16:17], s[12:13]
	s_cbranch_execz .LBB0_968
	v_mul_f32_e32 v48, v152, v112
	v_mul_f32_e32 v48, v48, v164
	v_bfe_u32 v113, v48, 16, 1
	s_lshl_b32 s46, s45, 13
	v_add3_u32 v48, v48, v113, s42
	v_lshl_add_u64 v[128:129], v[18:19], 0, s[46:47]
	global_store_short_d16_hi v[128:129], v48, off
.LBB0_968:
	s_or_b64 exec, exec, s[16:17]
	v_mul_f32_e32 v48, 0x4b800000, v49
	v_cndmask_b32_e64 v48, v49, v48, s[14:15]
	v_rsq_f32_e32 v48, v48
	s_or_b32 s41, s80, 11
	v_mul_f32_e32 v49, 0x45800000, v48
	v_cndmask_b32_e64 v48, v48, v49, s[14:15]
	v_mul_f32_e32 v113, 0x3f4ccccd, v48
	v_cmp_lt_u32_e64 s[14:15], s41, v166
	s_and_saveexec_b64 s[16:17], s[14:15]
	s_cbranch_execz .LBB0_970
	v_mul_f32_e32 v48, v153, v113
	v_mul_f32_e32 v48, v48, v164
	v_bfe_u32 v49, v48, 16, 1
	s_lshl_b32 s46, s41, 13
	v_add3_u32 v128, v48, v49, s42
	v_lshl_add_u64 v[48:49], v[18:19], 0, s[46:47]
	global_store_short_d16_hi v[48:49], v128, off
.LBB0_970:
	s_or_b64 exec, exec, s[16:17]
	v_pk_add_f32 v[48:49], v[150:151], v[168:169]
	s_or_b32 s59, s80, 16
	v_pk_fma_f32 v[48:49], v[48:49], s[2:3], v[210:211] op_sel_hi:[1,0,0]
	s_nop 0
	v_mul_f32_e32 v128, 0x4b800000, v48
	v_cmp_gt_f32_e64 s[16:17], s92, v48
	v_cmp_gt_f32_e64 s[18:19], s92, v49
	s_nop 0
	v_cndmask_b32_e64 v48, v48, v128, s[16:17]
	v_rsq_f32_e32 v48, v48
	s_nop 0
	v_mul_f32_e32 v128, 0x45800000, v48
	v_cndmask_b32_e64 v48, v48, v128, s[16:17]
	v_mul_f32_e32 v128, 0x3f4ccccd, v48
	v_cmp_lt_u32_e64 s[16:17], s59, v166
	s_and_saveexec_b64 s[20:21], s[16:17]
	s_cbranch_execz .LBB0_972
	v_mul_f32_e32 v48, v146, v128
	v_mul_f32_e32 v48, v48, v164
	v_bfe_u32 v129, v48, 16, 1
	s_lshl_b32 s46, s59, 13
	v_add3_u32 v48, v48, v129, s42
	v_lshl_add_u64 v[140:141], v[18:19], 0, s[46:47]
	global_store_short_d16_hi v[140:141], v48, off
; __device__ __forceinline__ unsigned f2bf(float f) { unsigned u = __builtin_bit_cast(unsigned, f); return (u + 0x7fffu + ((u >> 16) & 1u)) >> 16; }
; __device__ __forceinline__ void dattn_unit(const bf16* __restrict__ Qb, const bf16* __restrict__ Kh, const bf16* __restrict__ Vh, int nq, int kv_lo, int kv_hi, int NT, ...
;     ...
;     for (int d = 0; d < 8; ++d) { const float g = gnorm[32 * d + r32];
; #pragma unroll
;       for (int r = 0; r < 16; ++r) { const int rk = rg * 32 + (r & 3) + 8 * (r >> 2);
;           if (rk + 4 * hi < nq) *(unsigned short*)((unsigned char*)outp + (size_t)rk * 8192 + 64 * d + (unsigned)(hi * (4 * 8192) + r32 * 2)) = (unsigned short)f2bf(o[d][r] * ss[r] * g); } }
.LBB0_972:
	s_or_b64 exec, exec, s[20:21]
	v_mul_f32_e32 v48, 0x4b800000, v49
	v_cndmask_b32_e64 v48, v49, v48, s[18:19]
	v_rsq_f32_e32 v48, v48
	s_or_b32 s2, s80, 17
	v_mul_f32_e32 v49, 0x45800000, v48
	v_cndmask_b32_e64 v48, v48, v49, s[18:19]
	v_mul_f32_e32 v129, 0x3f4ccccd, v48
	v_cmp_lt_u32_e64 s[18:19], s2, v166
	s_and_saveexec_b64 s[20:21], s[18:19]
	s_cbranch_execz .LBB0_974
	v_mul_f32_e32 v48, v147, v129
	v_mul_f32_e32 v48, v48, v164
	v_bfe_u32 v49, v48, 16, 1
	s_lshl_b32 s46, s2, 13
	v_add3_u32 v140, v48, v49, s42
	v_lshl_add_u64 v[48:49], v[18:19], 0, s[46:47]
	global_store_short_d16_hi v[48:49], v140, off
.LBB0_974:
	s_or_b64 exec, exec, s[20:21]
	v_pk_add_f32 v[48:49], v[142:143], v[144:145]
	s_mov_b32 s20, 0x3b800000
	v_pk_fma_f32 v[48:49], v[48:49], s[20:21], v[210:211] op_sel_hi:[1,0,0]
	s_or_b32 s88, s80, 18
	v_mul_f32_e32 v140, 0x4b800000, v48
	v_cmp_gt_f32_e64 s[20:21], s92, v48
	v_cmp_gt_f32_e64 s[22:23], s92, v49
	s_nop 0
	v_cndmask_b32_e64 v48, v48, v140, s[20:21]
	v_rsq_f32_e32 v48, v48
	s_nop 0
	v_mul_f32_e32 v140, 0x45800000, v48
	v_cndmask_b32_e64 v48, v48, v140, s[20:21]
	v_mul_f32_e32 v140, 0x3f4ccccd, v48
	v_cmp_lt_u32_e64 s[20:21], s88, v166
	s_and_saveexec_b64 s[24:25], s[20:21]
	s_cbranch_execz .LBB0_976
	v_mul_f32_e32 v48, v148, v140
	v_mul_f32_e32 v48, v48, v164
	v_bfe_u32 v141, v48, 16, 1
	s_lshl_b32 s46, s88, 13
	v_add3_u32 v48, v48, v141, s42
	v_lshl_add_u64 v[142:143], v[18:19], 0, s[46:47]
	global_store_short_d16_hi v[142:143], v48, off
.LBB0_976:
	s_or_b64 exec, exec, s[24:25]
	v_mul_f32_e32 v48, 0x4b800000, v49
	v_cndmask_b32_e64 v48, v49, v48, s[22:23]
	v_rsq_f32_e32 v48, v48
	s_or_b32 s89, s80, 19
	v_mul_f32_e32 v49, 0x45800000, v48
	v_cndmask_b32_e64 v48, v48, v49, s[22:23]
	v_mul_f32_e32 v141, 0x3f4ccccd, v48
	v_cmp_lt_u32_e64 s[22:23], s89, v166
	s_and_saveexec_b64 s[24:25], s[22:23]
	s_cbranch_execz .LBB0_978
	v_mul_f32_e32 v48, v149, v141
	v_mul_f32_e32 v48, v48, v164
	v_bfe_u32 v49, v48, 16, 1
	s_lshl_b32 s46, s89, 13
	v_add3_u32 v142, v48, v49, s42
	v_lshl_add_u64 v[48:49], v[18:19], 0, s[46:47]
	global_store_short_d16_hi v[48:49], v142, off
.LBB0_978:
	s_or_b64 exec, exec, s[24:25]
	v_pk_add_f32 v[48:49], v[96:97], v[126:127]
	s_mov_b32 s24, 0x3b800000
	v_pk_fma_f32 v[48:49], v[48:49], s[24:25], v[210:211] op_sel_hi:[1,0,0]
	s_or_b32 s90, s80, 24
	v_mul_f32_e32 v96, 0x4b800000, v48
	v_cmp_gt_f32_e64 s[24:25], s92, v48
	v_cmp_gt_f32_e64 s[26:27], s92, v49
	s_nop 0
	v_cndmask_b32_e64 v48, v48, v96, s[24:25]
	v_rsq_f32_e32 v48, v48
	s_nop 0
	v_mul_f32_e32 v96, 0x45800000, v48
	v_cndmask_b32_e64 v48, v48, v96, s[24:25]
	v_mul_f32_e32 v48, 0x3f4ccccd, v48
	v_cmp_lt_u32_e64 s[24:25], s90, v166
	s_and_saveexec_b64 s[28:29], s[24:25]
	s_cbranch_execz .LBB0_980
	v_mul_f32_e32 v96, v124, v48
	v_mul_f32_e32 v96, v96, v164
	v_bfe_u32 v97, v96, 16, 1
	s_lshl_b32 s46, s90, 13
	v_add3_u32 v124, v96, v97, s42
	v_lshl_add_u64 v[96:97], v[18:19], 0, s[46:47]
	global_store_short_d16_hi v[96:97], v124, off
.LBB0_980:
	s_or_b64 exec, exec, s[28:29]
	v_mul_f32_e32 v96, 0x4b800000, v49
	v_cndmask_b32_e64 v49, v49, v96, s[26:27]
	v_rsq_f32_e32 v49, v49
	s_or_b32 s61, s80, 25
	v_mul_f32_e32 v96, 0x45800000, v49
	v_cndmask_b32_e64 v49, v49, v96, s[26:27]
	v_mul_f32_e32 v49, 0x3f4ccccd, v49
	v_cmp_lt_u32_e64 s[26:27], s61, v166
	s_and_saveexec_b64 s[28:29], s[26:27]
	s_cbranch_execz .LBB0_982
	v_mul_f32_e32 v96, v125, v49
	v_mul_f32_e32 v96, v164, v96
	v_bfe_u32 v97, v96, 16, 1
	s_lshl_b32 s46, s61, 13
	v_add3_u32 v124, v96, v97, s42
	v_lshl_add_u64 v[96:97], v[18:19], 0, s[46:47]
	global_store_short_d16_hi v[96:97], v124, off
.LBB0_982:
	s_or_b64 exec, exec, s[28:29]
	v_pk_add_f32 v[16:17], v[16:17], v[32:33]
	s_mov_b32 s28, 0x3b800000
	v_pk_fma_f32 v[16:17], v[16:17], s[28:29], v[210:211] op_sel_hi:[1,0,0]
	s_or_b32 s60, s80, 26
	v_mul_f32_e32 v32, 0x4b800000, v16
	v_cmp_gt_f32_e64 s[28:29], s92, v16
	v_cmp_gt_f32_e64 s[30:31], s92, v17
	s_nop 0
	v_cndmask_b32_e64 v16, v16, v32, s[28:29]
	v_rsq_f32_e32 v16, v16
	s_nop 0
	v_mul_f32_e32 v32, 0x45800000, v16
	v_cndmask_b32_e64 v16, v16, v32, s[28:29]
	v_mul_f32_e32 v32, 0x3f4ccccd, v16
	v_cmp_lt_u32_e64 s[28:29], s60, v166
	s_and_saveexec_b64 s[38:39], s[28:29]
	s_cbranch_execz .LBB0_984
	v_mul_f32_e32 v16, v122, v32
	v_mul_f32_e32 v16, v164, v16
	v_bfe_u32 v33, v16, 16, 1
	s_lshl_b32 s46, s60, 13
	v_add3_u32 v16, v16, v33, s42
	v_lshl_add_u64 v[96:97], v[18:19], 0, s[46:47]
	global_store_short_d16_hi v[96:97], v16, off
.LBB0_984:
	s_or_b64 exec, exec, s[38:39]
	v_mul_f32_e32 v16, 0x4b800000, v17
	v_cndmask_b32_e64 v16, v17, v16, s[30:31]
	v_rsq_f32_e32 v16, v16
	s_or_b32 s80, s80, 27
	v_mul_f32_e32 v17, 0x45800000, v16
	v_cndmask_b32_e64 v16, v16, v17, s[30:31]
	v_mul_f32_e32 v33, 0x3f4ccccd, v16
	v_cmp_lt_u32_e64 s[30:31], s80, v166
	s_and_saveexec_b64 s[38:39], s[30:31]
	s_cbranch_execz .LBB0_986
	v_mul_f32_e32 v16, v123, v33
	v_mul_f32_e32 v16, v164, v16
	v_bfe_u32 v17, v16, 16, 1
	s_lshl_b32 s46, s80, 13
	v_add3_u32 v96, v16, v17, s42
	v_lshl_add_u64 v[16:17], v[18:19], 0, s[46:47]
	global_store_short_d16_hi v[16:17], v96, off
.LBB0_986:
	s_or_b64 exec, exec, s[38:39]
	v_readlane_b32 s64, v253, 16
	v_readlane_b32 s72, v253, 24
	v_readlane_b32 s73, v253, 25
	v_readlane_b32 s65, v253, 17
	v_readlane_b32 s66, v253, 18
	v_lshl_add_u64 v[16:17], s[72:73], 0, v[0:1]
	v_mov_b32_e32 v0, v240
	v_readlane_b32 s67, v253, 19
	v_readlane_b32 s68, v253, 20
	v_readlane_b32 s69, v253, 21
	v_readlane_b32 s70, v253, 22
	v_readlane_b32 s71, v253, 23
	v_readlane_b32 s74, v253, 26
	v_readlane_b32 s75, v253, 27
	v_readlane_b32 s76, v253, 28
	v_readlane_b32 s77, v253, 29
	v_readlane_b32 s78, v253, 30
	v_readlane_b32 s79, v253, 31
	s_and_saveexec_b64 s[38:39], vcc
	s_cbranch_execnz .LBB0_1162
	s_or_b64 exec, exec, s[38:39]
	s_and_saveexec_b64 s[38:39], s[0:1]
	s_cbranch_execnz .LBB0_1163

; __device__ __forceinline__ unsigned f2bf(float f) { unsigned u = __builtin_bit_cast(unsigned, f); return (u + 0x7fffu + ((u >> 16) & 1u)) >> 16; }
; __device__ __forceinline__ void dattn_unit(const bf16* __restrict__ Qb, const bf16* __restrict__ Kh, const bf16* __restrict__ Vh, int nq, int kv_lo, int kv_hi, int NT, ...
;     ...
;     for (int d = 0; d < 8; ++d) { const float g = gnorm[32 * d + r32];
; #pragma unroll
;       for (int r = 0; r < 16; ++r) { const int rk = rg * 32 + (r & 3) + 8 * (r >> 2);
;           if (rk + 4 * hi < nq) *(unsigned short*)((unsigned char*)outp + (size_t)rk * 8192 + 64 * d + (unsigned)(hi * (4 * 8192) + r32 * 2)) = (unsigned short)f2bf(o[d][r] * ss[r] * g); } }
.LBB0_1002:
	s_or_b64 exec, exec, s[38:39]
	v_mov_b32_e32 v0, v241
	s_and_saveexec_b64 s[38:39], vcc
	s_cbranch_execnz .LBB0_1178

; __device__ __forceinline__ unsigned f2bf(float f) { unsigned u = __builtin_bit_cast(unsigned, f); return (u + 0x7fffu + ((u >> 16) & 1u)) >> 16; }
; __device__ __forceinline__ void dattn_unit(const bf16* __restrict__ Qb, const bf16* __restrict__ Kh, const bf16* __restrict__ Vh, int nq, int kv_lo, int kv_hi, int NT, ...
;     ...
;     for (int d = 0; d < 8; ++d) { const float g = gnorm[32 * d + r32];
; #pragma unroll
;       for (int r = 0; r < 16; ++r) { const int rk = rg * 32 + (r & 3) + 8 * (r >> 2);
;           if (rk + 4 * hi < nq) *(unsigned short*)((unsigned char*)outp + (size_t)rk * 8192 + 64 * d + (unsigned)(hi * (4 * 8192) + r32 * 2)) = (unsigned short)f2bf(o[d][r] * ss[r] * g); } }
.LBB0_1018:
	s_or_b64 exec, exec, s[38:39]
	v_mov_b32_e32 v0, v242
	s_and_saveexec_b64 s[38:39], vcc
	s_cbranch_execnz .LBB0_1194

; __device__ __forceinline__ unsigned f2bf(float f) { unsigned u = __builtin_bit_cast(unsigned, f); return (u + 0x7fffu + ((u >> 16) & 1u)) >> 16; }
; __device__ __forceinline__ void dattn_unit(const bf16* __restrict__ Qb, const bf16* __restrict__ Kh, const bf16* __restrict__ Vh, int nq, int kv_lo, int kv_hi, int NT, ...
;     ...
;     for (int d = 0; d < 8; ++d) { const float g = gnorm[32 * d + r32];
; #pragma unroll
;       for (int r = 0; r < 16; ++r) { const int rk = rg * 32 + (r & 3) + 8 * (r >> 2);
;           if (rk + 4 * hi < nq) *(unsigned short*)((unsigned char*)outp + (size_t)rk * 8192 + 64 * d + (unsigned)(hi * (4 * 8192) + r32 * 2)) = (unsigned short)f2bf(o[d][r] * ss[r] * g); } }
.LBB0_1034:
	s_or_b64 exec, exec, s[38:39]
	v_mov_b32_e32 v0, v243
	s_and_saveexec_b64 s[38:39], vcc
	s_cbranch_execnz .LBB0_1210

; __device__ __forceinline__ unsigned f2bf(float f) { unsigned u = __builtin_bit_cast(unsigned, f); return (u + 0x7fffu + ((u >> 16) & 1u)) >> 16; }
; __device__ __forceinline__ void dattn_unit(const bf16* __restrict__ Qb, const bf16* __restrict__ Kh, const bf16* __restrict__ Vh, int nq, int kv_lo, int kv_hi, int NT, ...
;     ...
;     for (int d = 0; d < 8; ++d) { const float g = gnorm[32 * d + r32];
; #pragma unroll
;       for (int r = 0; r < 16; ++r) { const int rk = rg * 32 + (r & 3) + 8 * (r >> 2);
;           if (rk + 4 * hi < nq) *(unsigned short*)((unsigned char*)outp + (size_t)rk * 8192 + 64 * d + (unsigned)(hi * (4 * 8192) + r32 * 2)) = (unsigned short)f2bf(o[d][r] * ss[r] * g); } }
.LBB0_1050:
	s_or_b64 exec, exec, s[38:39]
	v_mov_b32_e32 v0, v244
	s_and_saveexec_b64 s[38:39], vcc
	s_cbranch_execnz .LBB0_1226

; __device__ __forceinline__ unsigned f2bf(float f) { unsigned u = __builtin_bit_cast(unsigned, f); return (u + 0x7fffu + ((u >> 16) & 1u)) >> 16; }
; __device__ __forceinline__ void dattn_unit(const bf16* __restrict__ Qb, const bf16* __restrict__ Kh, const bf16* __restrict__ Vh, int nq, int kv_lo, int kv_hi, int NT, ...
;     ...
;     for (int d = 0; d < 8; ++d) { const float g = gnorm[32 * d + r32];
; #pragma unroll
;       for (int r = 0; r < 16; ++r) { const int rk = rg * 32 + (r & 3) + 8 * (r >> 2);
;           if (rk + 4 * hi < nq) *(unsigned short*)((unsigned char*)outp + (size_t)rk * 8192 + 64 * d + (unsigned)(hi * (4 * 8192) + r32 * 2)) = (unsigned short)f2bf(o[d][r] * ss[r] * g); } }
.LBB0_1066:
	s_or_b64 exec, exec, s[38:39]
	v_mov_b32_e32 v0, v245
	s_and_saveexec_b64 s[38:39], vcc
	s_cbranch_execnz .LBB0_1242

; __device__ __forceinline__ unsigned f2bf(float f) { unsigned u = __builtin_bit_cast(unsigned, f); return (u + 0x7fffu + ((u >> 16) & 1u)) >> 16; }
; __device__ __forceinline__ void dattn_unit(const bf16* __restrict__ Qb, const bf16* __restrict__ Kh, const bf16* __restrict__ Vh, int nq, int kv_lo, int kv_hi, int NT, ...
;     ...
;     for (int d = 0; d < 8; ++d) { const float g = gnorm[32 * d + r32];
; #pragma unroll
;       for (int r = 0; r < 16; ++r) { const int rk = rg * 32 + (r & 3) + 8 * (r >> 2);
;           if (rk + 4 * hi < nq) *(unsigned short*)((unsigned char*)outp + (size_t)rk * 8192 + 64 * d + (unsigned)(hi * (4 * 8192) + r32 * 2)) = (unsigned short)f2bf(o[d][r] * ss[r] * g); } }
.LBB0_1082:
	s_or_b64 exec, exec, s[38:39]
	v_mov_b32_e32 v0, v246
	s_and_saveexec_b64 s[38:39], vcc
	s_cbranch_execnz .LBB0_1258

; __device__ __forceinline__ unsigned f2bf(float f) { unsigned u = __builtin_bit_cast(unsigned, f); return (u + 0x7fffu + ((u >> 16) & 1u)) >> 16; }
; __device__ __forceinline__ void dattn_unit(const bf16* __restrict__ Qb, const bf16* __restrict__ Kh, const bf16* __restrict__ Vh, int nq, int kv_lo, int kv_hi, int NT, ...
;     ...
;       for (int r = 0; r < 16; ++r) { const int rk = rg * 32 + (r & 3) + 8 * (r >> 2);
;           if (rk + 4 * hi < nq) *(unsigned short*)((unsigned char*)outp + (size_t)rk * 8192 + 64 * d + (unsigned)(hi * (4 * 8192) + r32 * 2)) = (unsigned short)f2bf(o[d][r] * ss[r] * g); } }
.LBB0_1098:
	v_mul_f32_e32 v2, v13, v33
	v_mul_f32_e32 v0, v2, v0
	v_bfe_u32 v2, v0, 16, 1
	s_lshl_b32 s46, s80, 13
	v_add3_u32 v0, v0, v2, s42
	v_lshl_add_u64 v[2:3], v[18:19], 0, s[46:47]
	global_store_short_d16_hi v[2:3], v0, off offset:448

; __device__ __forceinline__ unsigned f2bf(float f) { unsigned u = __builtin_bit_cast(unsigned, f); return (u + 0x7fffu + ((u >> 16) & 1u)) >> 16; }
; __device__ __forceinline__ void dattn_unit(const bf16* __restrict__ Qb, const bf16* __restrict__ Kh, const bf16* __restrict__ Vh, int nq, int kv_lo, int kv_hi, int NT, ...
;     ...
;     for (int d = 0; d < 8; ++d) { const float g = gnorm[32 * d + r32];
; #pragma unroll
;       for (int r = 0; r < 16; ++r) { const int rk = rg * 32 + (r & 3) + 8 * (r >> 2);
;           if (rk + 4 * hi < nq) *(unsigned short*)((unsigned char*)outp + (size_t)rk * 8192 + 64 * d + (unsigned)(hi * (4 * 8192) + r32 * 2)) = (unsigned short)f2bf(o[d][r] * ss[r] * g); } }
.LBB0_1162:
	v_mul_f32_e32 v96, v132, v64
	v_mul_f32_e32 v96, v96, v0
	v_bfe_u32 v97, v96, 16, 1
	s_lshl_b32 s46, s83, 18
	v_add3_u32 v122, v96, v97, s42
	v_lshl_add_u64 v[96:97], v[18:19], 0, s[46:47]
	global_store_short_d16_hi v[96:97], v122, off offset:64
	s_or_b64 exec, exec, s[38:39]
	s_and_saveexec_b64 s[38:39], s[0:1]
	s_cbranch_execz .LBB0_988
.LBB0_1163:
	v_mul_f32_e32 v96, v133, v65
	v_mul_f32_e32 v96, v96, v0
	v_bfe_u32 v97, v96, 16, 1
	s_lshl_b32 s46, s81, 13
	v_add3_u32 v122, v96, v97, s42
	v_lshl_add_u64 v[96:97], v[18:19], 0, s[46:47]
	global_store_short_d16_hi v[96:97], v122, off offset:64
	s_or_b64 exec, exec, s[38:39]
	s_and_saveexec_b64 s[38:39], s[4:5]
	s_cbranch_execz .LBB0_989
.LBB0_1164:
	v_mul_f32_e32 v96, v136, v80
	v_mul_f32_e32 v96, v96, v0
	v_bfe_u32 v97, v96, 16, 1
	s_lshl_b32 s46, s44, 13
	v_add3_u32 v122, v96, v97, s42
	v_lshl_add_u64 v[96:97], v[18:19], 0, s[46:47]
	global_store_short_d16_hi v[96:97], v122, off offset:64
	s_or_b64 exec, exec, s[38:39]
	s_and_saveexec_b64 s[38:39], s[6:7]
	s_cbranch_execz .LBB0_990
.LBB0_1165:
	v_mul_f32_e32 v96, v137, v81
	v_mul_f32_e32 v96, v96, v0
	v_bfe_u32 v97, v96, 16, 1
	s_lshl_b32 s46, s93, 13
	v_add3_u32 v122, v96, v97, s42
	v_lshl_add_u64 v[96:97], v[18:19], 0, s[46:47]
	global_store_short_d16_hi v[96:97], v122, off offset:64
	s_or_b64 exec, exec, s[38:39]
	s_and_saveexec_b64 s[38:39], s[8:9]
	s_cbranch_execz .LBB0_991
.LBB0_1166:
	v_mul_f32_e32 v96, v134, v138
	v_mul_f32_e32 v96, v96, v0
	v_bfe_u32 v97, v96, 16, 1
	s_lshl_b32 s46, s50, 13
	v_add3_u32 v122, v96, v97, s42
	v_lshl_add_u64 v[96:97], v[18:19], 0, s[46:47]
	global_store_short_d16_hi v[96:97], v122, off offset:64
	s_or_b64 exec, exec, s[38:39]
	s_and_saveexec_b64 s[38:39], s[10:11]
	s_cbranch_execz .LBB0_992
.LBB0_1167:
	v_mul_f32_e32 v96, v135, v139
	v_mul_f32_e32 v96, v96, v0
	v_bfe_u32 v97, v96, 16, 1
	s_lshl_b32 s46, s58, 13
	v_add3_u32 v122, v96, v97, s42
	v_lshl_add_u64 v[96:97], v[18:19], 0, s[46:47]
	global_store_short_d16_hi v[96:97], v122, off offset:64
	s_or_b64 exec, exec, s[38:39]
	s_and_saveexec_b64 s[38:39], s[12:13]
	s_cbranch_execz .LBB0_993
.LBB0_1168:
	v_mul_f32_e32 v96, v118, v112
	v_mul_f32_e32 v96, v96, v0
	v_bfe_u32 v97, v96, 16, 1
	s_lshl_b32 s46, s45, 13
	v_add3_u32 v118, v96, v97, s42
	v_lshl_add_u64 v[96:97], v[18:19], 0, s[46:47]
	global_store_short_d16_hi v[96:97], v118, off offset:64
	s_or_b64 exec, exec, s[38:39]
	s_and_saveexec_b64 s[38:39], s[14:15]
	s_cbranch_execz .LBB0_994
.LBB0_1169:
	v_mul_f32_e32 v96, v119, v113
	v_mul_f32_e32 v96, v96, v0
	v_bfe_u32 v97, v96, 16, 1
	s_lshl_b32 s46, s41, 13
	v_add3_u32 v118, v96, v97, s42
	v_lshl_add_u64 v[96:97], v[18:19], 0, s[46:47]
	global_store_short_d16_hi v[96:97], v118, off offset:64
	s_or_b64 exec, exec, s[38:39]
	s_and_saveexec_b64 s[38:39], s[16:17]
	s_cbranch_execz .LBB0_995
.LBB0_1170:
	v_mul_f32_e32 v96, v106, v128
	v_mul_f32_e32 v96, v96, v0
	v_bfe_u32 v97, v96, 16, 1
	s_lshl_b32 s46, s59, 13
	v_add3_u32 v106, v96, v97, s42
	v_lshl_add_u64 v[96:97], v[18:19], 0, s[46:47]
	global_store_short_d16_hi v[96:97], v106, off offset:64
	s_or_b64 exec, exec, s[38:39]
	s_and_saveexec_b64 s[38:39], s[18:19]
	s_cbranch_execz .LBB0_996
.LBB0_1171:
	v_mul_f32_e32 v96, v107, v129
	v_mul_f32_e32 v96, v96, v0
	v_bfe_u32 v97, v96, 16, 1
	s_lshl_b32 s46, s2, 13
	v_add3_u32 v106, v96, v97, s42
	v_lshl_add_u64 v[96:97], v[18:19], 0, s[46:47]
	global_store_short_d16_hi v[96:97], v106, off offset:64
	s_or_b64 exec, exec, s[38:39]
	s_and_saveexec_b64 s[38:39], s[20:21]
	s_cbranch_execz .LBB0_997
.LBB0_1172:
	v_mul_f32_e32 v96, v120, v140
	v_mul_f32_e32 v96, v96, v0
	v_bfe_u32 v97, v96, 16, 1
	s_lshl_b32 s46, s88, 13
	v_add3_u32 v106, v96, v97, s42
	v_lshl_add_u64 v[96:97], v[18:19], 0, s[46:47]
	global_store_short_d16_hi v[96:97], v106, off offset:64
	s_or_b64 exec, exec, s[38:39]
	s_and_saveexec_b64 s[38:39], s[22:23]
	s_cbranch_execz .LBB0_998
.LBB0_1173:
	v_mul_f32_e32 v96, v121, v141
	v_mul_f32_e32 v96, v96, v0
	v_bfe_u32 v97, v96, 16, 1
	s_lshl_b32 s46, s89, 13
	v_add3_u32 v106, v96, v97, s42
	v_lshl_add_u64 v[96:97], v[18:19], 0, s[46:47]
	global_store_short_d16_hi v[96:97], v106, off offset:64
	s_or_b64 exec, exec, s[38:39]
	s_and_saveexec_b64 s[38:39], s[24:25]
	s_cbranch_execz .LBB0_999
.LBB0_1174:
	v_mul_f32_e32 v96, v110, v48
	v_mul_f32_e32 v96, v96, v0
	v_bfe_u32 v97, v96, 16, 1
	s_lshl_b32 s46, s90, 13
	v_add3_u32 v106, v96, v97, s42
	v_lshl_add_u64 v[96:97], v[18:19], 0, s[46:47]
	global_store_short_d16_hi v[96:97], v106, off offset:64
	s_or_b64 exec, exec, s[38:39]
	s_and_saveexec_b64 s[38:39], s[26:27]
	s_cbranch_execz .LBB0_1000
.LBB0_1175:
	v_mul_f32_e32 v96, v111, v49
	v_mul_f32_e32 v96, v96, v0
	v_bfe_u32 v97, v96, 16, 1
	s_lshl_b32 s46, s61, 13
	v_add3_u32 v106, v96, v97, s42
	v_lshl_add_u64 v[96:97], v[18:19], 0, s[46:47]
	global_store_short_d16_hi v[96:97], v106, off offset:64
	s_or_b64 exec, exec, s[38:39]
	s_and_saveexec_b64 s[38:39], s[28:29]
	s_cbranch_execz .LBB0_1001
.LBB0_1176:
	v_mul_f32_e32 v96, v108, v32
	v_mul_f32_e32 v96, v96, v0
	v_bfe_u32 v97, v96, 16, 1
	s_lshl_b32 s46, s60, 13
	v_add3_u32 v106, v96, v97, s42
	v_lshl_add_u64 v[96:97], v[18:19], 0, s[46:47]
	global_store_short_d16_hi v[96:97], v106, off offset:64
	s_or_b64 exec, exec, s[38:39]
	s_and_saveexec_b64 s[38:39], s[30:31]
	s_cbranch_execz .LBB0_1002
.LBB0_1177:
	v_mul_f32_e32 v96, v109, v33
	v_mul_f32_e32 v0, v96, v0
	v_bfe_u32 v96, v0, 16, 1
	s_lshl_b32 s46, s80, 13
	v_add3_u32 v0, v0, v96, s42
	v_lshl_add_u64 v[96:97], v[18:19], 0, s[46:47]
	global_store_short_d16_hi v[96:97], v0, off offset:64
	s_or_b64 exec, exec, s[38:39]
	v_mov_b32_e32 v0, v241
	s_and_saveexec_b64 s[38:39], vcc
	s_cbranch_execz .LBB0_1003
; __device__ __forceinline__ unsigned f2bf(float f) { unsigned u = __builtin_bit_cast(unsigned, f); return (u + 0x7fffu + ((u >> 16) & 1u)) >> 16; }
; __device__ __forceinline__ void dattn_unit(const bf16* __restrict__ Qb, const bf16* __restrict__ Kh, const bf16* __restrict__ Vh, int nq, int kv_lo, int kv_hi, int NT, ...
;     ...
;     for (int d = 0; d < 8; ++d) { const float g = gnorm[32 * d + r32];
; #pragma unroll
;       for (int r = 0; r < 16; ++r) { const int rk = rg * 32 + (r & 3) + 8 * (r >> 2);
;           if (rk + 4 * hi < nq) *(unsigned short*)((unsigned char*)outp + (size_t)rk * 8192 + 64 * d + (unsigned)(hi * (4 * 8192) + r32 * 2)) = (unsigned short)f2bf(o[d][r] * ss[r] * g); } }
.LBB0_1178:
	v_mul_f32_e32 v96, v130, v64
	v_mul_f32_e32 v96, v96, v0
	v_bfe_u32 v97, v96, 16, 1
	s_lshl_b32 s46, s83, 18
	v_add3_u32 v106, v96, v97, s42
	v_lshl_add_u64 v[96:97], v[18:19], 0, s[46:47]
	global_store_short_d16_hi v[96:97], v106, off offset:128
	s_or_b64 exec, exec, s[38:39]
	s_and_saveexec_b64 s[38:39], s[0:1]
	s_cbranch_execz .LBB0_1004
.LBB0_1179:
	v_mul_f32_e32 v96, v131, v65
	v_mul_f32_e32 v96, v96, v0
	v_bfe_u32 v97, v96, 16, 1
	s_lshl_b32 s46, s81, 13
	v_add3_u32 v106, v96, v97, s42
	v_lshl_add_u64 v[96:97], v[18:19], 0, s[46:47]
	global_store_short_d16_hi v[96:97], v106, off offset:128
	s_or_b64 exec, exec, s[38:39]
	s_and_saveexec_b64 s[38:39], s[4:5]
	s_cbranch_execz .LBB0_1005
.LBB0_1180:
	v_mul_f32_e32 v96, v116, v80
	v_mul_f32_e32 v96, v96, v0
	v_bfe_u32 v97, v96, 16, 1
	s_lshl_b32 s46, s44, 13
	v_add3_u32 v106, v96, v97, s42
	v_lshl_add_u64 v[96:97], v[18:19], 0, s[46:47]
	global_store_short_d16_hi v[96:97], v106, off offset:128
	s_or_b64 exec, exec, s[38:39]
	s_and_saveexec_b64 s[38:39], s[6:7]
	s_cbranch_execz .LBB0_1006
.LBB0_1181:
	v_mul_f32_e32 v96, v117, v81
	v_mul_f32_e32 v96, v96, v0
	v_bfe_u32 v97, v96, 16, 1
	s_lshl_b32 s46, s93, 13
	v_add3_u32 v106, v96, v97, s42
	v_lshl_add_u64 v[96:97], v[18:19], 0, s[46:47]
	global_store_short_d16_hi v[96:97], v106, off offset:128
	s_or_b64 exec, exec, s[38:39]
	s_and_saveexec_b64 s[38:39], s[8:9]
	s_cbranch_execz .LBB0_1007
.LBB0_1182:
	v_mul_f32_e32 v96, v102, v138
	v_mul_f32_e32 v96, v96, v0
	v_bfe_u32 v97, v96, 16, 1
	s_lshl_b32 s46, s50, 13
	v_add3_u32 v102, v96, v97, s42
	v_lshl_add_u64 v[96:97], v[18:19], 0, s[46:47]
	global_store_short_d16_hi v[96:97], v102, off offset:128
	s_or_b64 exec, exec, s[38:39]
	s_and_saveexec_b64 s[38:39], s[10:11]
	s_cbranch_execz .LBB0_1008
.LBB0_1183:
	v_mul_f32_e32 v96, v103, v139
	v_mul_f32_e32 v96, v96, v0
	v_bfe_u32 v97, v96, 16, 1
	s_lshl_b32 s46, s58, 13
	v_add3_u32 v102, v96, v97, s42
	v_lshl_add_u64 v[96:97], v[18:19], 0, s[46:47]
	global_store_short_d16_hi v[96:97], v102, off offset:128
	s_or_b64 exec, exec, s[38:39]
	s_and_saveexec_b64 s[38:39], s[12:13]
	s_cbranch_execz .LBB0_1009
.LBB0_1184:
	v_mul_f32_e32 v96, v100, v112
	v_mul_f32_e32 v96, v96, v0
	v_bfe_u32 v97, v96, 16, 1
	s_lshl_b32 s46, s45, 13
	v_add3_u32 v100, v96, v97, s42
	v_lshl_add_u64 v[96:97], v[18:19], 0, s[46:47]
	global_store_short_d16_hi v[96:97], v100, off offset:128
	s_or_b64 exec, exec, s[38:39]
	s_and_saveexec_b64 s[38:39], s[14:15]
	s_cbranch_execz .LBB0_1010
.LBB0_1185:
	v_mul_f32_e32 v96, v101, v113
	v_mul_f32_e32 v96, v96, v0
	v_bfe_u32 v97, v96, 16, 1
	s_lshl_b32 s46, s41, 13
	v_add3_u32 v100, v96, v97, s42
	v_lshl_add_u64 v[96:97], v[18:19], 0, s[46:47]
	global_store_short_d16_hi v[96:97], v100, off offset:128
	s_or_b64 exec, exec, s[38:39]
	s_and_saveexec_b64 s[38:39], s[16:17]
	s_cbranch_execz .LBB0_1011
.LBB0_1186:
	v_mul_f32_e32 v90, v90, v128
	v_mul_f32_e32 v90, v90, v0
	v_bfe_u32 v96, v90, 16, 1
	s_lshl_b32 s46, s59, 13
	v_add3_u32 v90, v90, v96, s42
	v_lshl_add_u64 v[96:97], v[18:19], 0, s[46:47]
	global_store_short_d16_hi v[96:97], v90, off offset:128
	s_or_b64 exec, exec, s[38:39]
	s_and_saveexec_b64 s[38:39], s[18:19]
	s_cbranch_execz .LBB0_1012
.LBB0_1187:
	v_mul_f32_e32 v90, v91, v129
	v_mul_f32_e32 v90, v90, v0
	v_bfe_u32 v91, v90, 16, 1
	s_lshl_b32 s46, s2, 13
	v_add3_u32 v96, v90, v91, s42
	v_lshl_add_u64 v[90:91], v[18:19], 0, s[46:47]
	global_store_short_d16_hi v[90:91], v96, off offset:128
	s_or_b64 exec, exec, s[38:39]
	s_and_saveexec_b64 s[38:39], s[20:21]
	s_cbranch_execz .LBB0_1013
.LBB0_1188:
	v_mul_f32_e32 v90, v104, v140
	v_mul_f32_e32 v90, v90, v0
	v_bfe_u32 v91, v90, 16, 1
	s_lshl_b32 s46, s88, 13
	v_add3_u32 v96, v90, v91, s42
	v_lshl_add_u64 v[90:91], v[18:19], 0, s[46:47]
	global_store_short_d16_hi v[90:91], v96, off offset:128
	s_or_b64 exec, exec, s[38:39]
	s_and_saveexec_b64 s[38:39], s[22:23]
	s_cbranch_execz .LBB0_1014
.LBB0_1189:
	v_mul_f32_e32 v90, v105, v141
	v_mul_f32_e32 v90, v90, v0
	v_bfe_u32 v91, v90, 16, 1
	s_lshl_b32 s46, s89, 13
	v_add3_u32 v96, v90, v91, s42
	v_lshl_add_u64 v[90:91], v[18:19], 0, s[46:47]
	global_store_short_d16_hi v[90:91], v96, off offset:128
	s_or_b64 exec, exec, s[38:39]
	s_and_saveexec_b64 s[38:39], s[24:25]
	s_cbranch_execz .LBB0_1015
.LBB0_1190:
	v_mul_f32_e32 v90, v94, v48
	v_mul_f32_e32 v90, v90, v0
	v_bfe_u32 v91, v90, 16, 1
	s_lshl_b32 s46, s90, 13
	v_add3_u32 v94, v90, v91, s42
	v_lshl_add_u64 v[90:91], v[18:19], 0, s[46:47]
	global_store_short_d16_hi v[90:91], v94, off offset:128
	s_or_b64 exec, exec, s[38:39]
	s_and_saveexec_b64 s[38:39], s[26:27]
	s_cbranch_execz .LBB0_1016
.LBB0_1191:
	v_mul_f32_e32 v90, v95, v49
	v_mul_f32_e32 v90, v90, v0
	v_bfe_u32 v91, v90, 16, 1
	s_lshl_b32 s46, s61, 13
	v_add3_u32 v94, v90, v91, s42
	v_lshl_add_u64 v[90:91], v[18:19], 0, s[46:47]
	global_store_short_d16_hi v[90:91], v94, off offset:128
	s_or_b64 exec, exec, s[38:39]
	s_and_saveexec_b64 s[38:39], s[28:29]
	s_cbranch_execz .LBB0_1017
.LBB0_1192:
	v_mul_f32_e32 v90, v92, v32
	v_mul_f32_e32 v90, v90, v0
	v_bfe_u32 v91, v90, 16, 1
	s_lshl_b32 s46, s60, 13
	v_add3_u32 v92, v90, v91, s42
	v_lshl_add_u64 v[90:91], v[18:19], 0, s[46:47]
	global_store_short_d16_hi v[90:91], v92, off offset:128
	s_or_b64 exec, exec, s[38:39]
	s_and_saveexec_b64 s[38:39], s[30:31]
	s_cbranch_execz .LBB0_1018
.LBB0_1193:
	v_mul_f32_e32 v90, v93, v33
	v_mul_f32_e32 v0, v90, v0
	v_bfe_u32 v90, v0, 16, 1
	s_lshl_b32 s46, s80, 13
	v_add3_u32 v0, v0, v90, s42
	v_lshl_add_u64 v[90:91], v[18:19], 0, s[46:47]
	global_store_short_d16_hi v[90:91], v0, off offset:128
	s_or_b64 exec, exec, s[38:39]
	v_mov_b32_e32 v0, v242
	s_and_saveexec_b64 s[38:39], vcc
	s_cbranch_execz .LBB0_1019
; __device__ __forceinline__ unsigned f2bf(float f) { unsigned u = __builtin_bit_cast(unsigned, f); return (u + 0x7fffu + ((u >> 16) & 1u)) >> 16; }
; __device__ __forceinline__ void dattn_unit(const bf16* __restrict__ Qb, const bf16* __restrict__ Kh, const bf16* __restrict__ Vh, int nq, int kv_lo, int kv_hi, int NT, ...
;     ...
;     for (int d = 0; d < 8; ++d) { const float g = gnorm[32 * d + r32];
; #pragma unroll
;       for (int r = 0; r < 16; ++r) { const int rk = rg * 32 + (r & 3) + 8 * (r >> 2);
;           if (rk + 4 * hi < nq) *(unsigned short*)((unsigned char*)outp + (size_t)rk * 8192 + 64 * d + (unsigned)(hi * (4 * 8192) + r32 * 2)) = (unsigned short)f2bf(o[d][r] * ss[r] * g); } }
.LBB0_1194:
	v_mul_f32_e32 v90, v114, v64
	v_mul_f32_e32 v90, v90, v0
	v_bfe_u32 v91, v90, 16, 1
	s_lshl_b32 s46, s83, 18
	v_add3_u32 v92, v90, v91, s42
	v_lshl_add_u64 v[90:91], v[18:19], 0, s[46:47]
	global_store_short_d16_hi v[90:91], v92, off offset:192
	s_or_b64 exec, exec, s[38:39]
	s_and_saveexec_b64 s[38:39], s[0:1]
	s_cbranch_execz .LBB0_1020
.LBB0_1195:
	v_mul_f32_e32 v90, v115, v65
	v_mul_f32_e32 v90, v90, v0
	v_bfe_u32 v91, v90, 16, 1
	s_lshl_b32 s46, s81, 13
	v_add3_u32 v92, v90, v91, s42
	v_lshl_add_u64 v[90:91], v[18:19], 0, s[46:47]
	global_store_short_d16_hi v[90:91], v92, off offset:192
	s_or_b64 exec, exec, s[38:39]
	s_and_saveexec_b64 s[38:39], s[4:5]
	s_cbranch_execz .LBB0_1021
.LBB0_1196:
	v_mul_f32_e32 v90, v98, v80
	v_mul_f32_e32 v90, v90, v0
	v_bfe_u32 v91, v90, 16, 1
	s_lshl_b32 s46, s44, 13
	v_add3_u32 v92, v90, v91, s42
	v_lshl_add_u64 v[90:91], v[18:19], 0, s[46:47]
	global_store_short_d16_hi v[90:91], v92, off offset:192
	s_or_b64 exec, exec, s[38:39]
	s_and_saveexec_b64 s[38:39], s[6:7]
	s_cbranch_execz .LBB0_1022
.LBB0_1197:
	v_mul_f32_e32 v90, v99, v81
	v_mul_f32_e32 v90, v90, v0
	v_bfe_u32 v91, v90, 16, 1
	s_lshl_b32 s46, s93, 13
	v_add3_u32 v92, v90, v91, s42
	v_lshl_add_u64 v[90:91], v[18:19], 0, s[46:47]
	global_store_short_d16_hi v[90:91], v92, off offset:192
	s_or_b64 exec, exec, s[38:39]
	s_and_saveexec_b64 s[38:39], s[8:9]
	s_cbranch_execz .LBB0_1023
.LBB0_1198:
	v_mul_f32_e32 v84, v84, v138
	v_mul_f32_e32 v84, v84, v0
	v_bfe_u32 v90, v84, 16, 1
	s_lshl_b32 s46, s50, 13
	v_add3_u32 v84, v84, v90, s42
	v_lshl_add_u64 v[90:91], v[18:19], 0, s[46:47]
	global_store_short_d16_hi v[90:91], v84, off offset:192
	s_or_b64 exec, exec, s[38:39]
	s_and_saveexec_b64 s[38:39], s[10:11]
	s_cbranch_execz .LBB0_1024
.LBB0_1199:
	v_mul_f32_e32 v84, v85, v139
	v_mul_f32_e32 v84, v84, v0
	v_bfe_u32 v85, v84, 16, 1
	s_lshl_b32 s46, s58, 13
	v_add3_u32 v90, v84, v85, s42
	v_lshl_add_u64 v[84:85], v[18:19], 0, s[46:47]
	global_store_short_d16_hi v[84:85], v90, off offset:192
	s_or_b64 exec, exec, s[38:39]
	s_and_saveexec_b64 s[38:39], s[12:13]
	s_cbranch_execz .LBB0_1025
.LBB0_1200:
	v_mul_f32_e32 v82, v82, v112
	v_mul_f32_e32 v82, v82, v0
	v_bfe_u32 v84, v82, 16, 1
	s_lshl_b32 s46, s45, 13
	v_add3_u32 v82, v82, v84, s42
	v_lshl_add_u64 v[84:85], v[18:19], 0, s[46:47]
	global_store_short_d16_hi v[84:85], v82, off offset:192
	s_or_b64 exec, exec, s[38:39]
	s_and_saveexec_b64 s[38:39], s[14:15]
	s_cbranch_execz .LBB0_1026
.LBB0_1201:
	v_mul_f32_e32 v82, v83, v113
	v_mul_f32_e32 v82, v82, v0
	v_bfe_u32 v83, v82, 16, 1
	s_lshl_b32 s46, s41, 13
	v_add3_u32 v84, v82, v83, s42
	v_lshl_add_u64 v[82:83], v[18:19], 0, s[46:47]
	global_store_short_d16_hi v[82:83], v84, off offset:192
	s_or_b64 exec, exec, s[38:39]
	s_and_saveexec_b64 s[38:39], s[16:17]
	s_cbranch_execz .LBB0_1027
.LBB0_1202:
	v_mul_f32_e32 v82, v88, v128
	v_mul_f32_e32 v82, v82, v0
	v_bfe_u32 v83, v82, 16, 1
	s_lshl_b32 s46, s59, 13
	v_add3_u32 v84, v82, v83, s42
	v_lshl_add_u64 v[82:83], v[18:19], 0, s[46:47]
	global_store_short_d16_hi v[82:83], v84, off offset:192
	s_or_b64 exec, exec, s[38:39]
	s_and_saveexec_b64 s[38:39], s[18:19]
	s_cbranch_execz .LBB0_1028
.LBB0_1203:
	v_mul_f32_e32 v82, v89, v129
	v_mul_f32_e32 v82, v82, v0
	v_bfe_u32 v83, v82, 16, 1
	s_lshl_b32 s46, s2, 13
	v_add3_u32 v84, v82, v83, s42
	v_lshl_add_u64 v[82:83], v[18:19], 0, s[46:47]
	global_store_short_d16_hi v[82:83], v84, off offset:192
	s_or_b64 exec, exec, s[38:39]
	s_and_saveexec_b64 s[38:39], s[20:21]
	s_cbranch_execz .LBB0_1029
.LBB0_1204:
	v_mul_f32_e32 v82, v86, v140
	v_mul_f32_e32 v82, v82, v0
	v_bfe_u32 v83, v82, 16, 1
	s_lshl_b32 s46, s88, 13
	v_add3_u32 v84, v82, v83, s42
	v_lshl_add_u64 v[82:83], v[18:19], 0, s[46:47]
	global_store_short_d16_hi v[82:83], v84, off offset:192
	s_or_b64 exec, exec, s[38:39]
	s_and_saveexec_b64 s[38:39], s[22:23]
	s_cbranch_execz .LBB0_1030
.LBB0_1205:
	v_mul_f32_e32 v82, v87, v141
	v_mul_f32_e32 v82, v82, v0
	v_bfe_u32 v83, v82, 16, 1
	s_lshl_b32 s46, s89, 13
	v_add3_u32 v84, v82, v83, s42
	v_lshl_add_u64 v[82:83], v[18:19], 0, s[46:47]
	global_store_short_d16_hi v[82:83], v84, off offset:192
	s_or_b64 exec, exec, s[38:39]
	s_and_saveexec_b64 s[38:39], s[24:25]
	s_cbranch_execz .LBB0_1031
.LBB0_1206:
	v_mul_f32_e32 v78, v78, v48
	v_mul_f32_e32 v78, v78, v0
	v_bfe_u32 v82, v78, 16, 1
	s_lshl_b32 s46, s90, 13
	v_add3_u32 v78, v78, v82, s42
	v_lshl_add_u64 v[82:83], v[18:19], 0, s[46:47]
	global_store_short_d16_hi v[82:83], v78, off offset:192
	s_or_b64 exec, exec, s[38:39]
	s_and_saveexec_b64 s[38:39], s[26:27]
	s_cbranch_execz .LBB0_1032
.LBB0_1207:
	v_mul_f32_e32 v78, v79, v49
	v_mul_f32_e32 v78, v78, v0
	v_bfe_u32 v79, v78, 16, 1
	s_lshl_b32 s46, s61, 13
	v_add3_u32 v82, v78, v79, s42
	v_lshl_add_u64 v[78:79], v[18:19], 0, s[46:47]
	global_store_short_d16_hi v[78:79], v82, off offset:192
	s_or_b64 exec, exec, s[38:39]
	s_and_saveexec_b64 s[38:39], s[28:29]
	s_cbranch_execz .LBB0_1033
.LBB0_1208:
	v_mul_f32_e32 v76, v76, v32
	v_mul_f32_e32 v76, v76, v0
	v_bfe_u32 v78, v76, 16, 1
	s_lshl_b32 s46, s60, 13
	v_add3_u32 v76, v76, v78, s42
	v_lshl_add_u64 v[78:79], v[18:19], 0, s[46:47]
	global_store_short_d16_hi v[78:79], v76, off offset:192
	s_or_b64 exec, exec, s[38:39]
	s_and_saveexec_b64 s[38:39], s[30:31]
	s_cbranch_execz .LBB0_1034
.LBB0_1209:
	v_mul_f32_e32 v76, v77, v33
	v_mul_f32_e32 v0, v76, v0
	v_bfe_u32 v76, v0, 16, 1
	s_lshl_b32 s46, s80, 13
	v_add3_u32 v0, v0, v76, s42
	v_lshl_add_u64 v[76:77], v[18:19], 0, s[46:47]
	global_store_short_d16_hi v[76:77], v0, off offset:192
	s_or_b64 exec, exec, s[38:39]
	v_mov_b32_e32 v0, v243
	s_and_saveexec_b64 s[38:39], vcc
	s_cbranch_execz .LBB0_1035
; __device__ __forceinline__ unsigned f2bf(float f) { unsigned u = __builtin_bit_cast(unsigned, f); return (u + 0x7fffu + ((u >> 16) & 1u)) >> 16; }
; __device__ __forceinline__ void dattn_unit(const bf16* __restrict__ Qb, const bf16* __restrict__ Kh, const bf16* __restrict__ Vh, int nq, int kv_lo, int kv_hi, int NT, ...
;     ...
;     for (int d = 0; d < 8; ++d) { const float g = gnorm[32 * d + r32];
; #pragma unroll
;       for (int r = 0; r < 16; ++r) { const int rk = rg * 32 + (r & 3) + 8 * (r >> 2);
;           if (rk + 4 * hi < nq) *(unsigned short*)((unsigned char*)outp + (size_t)rk * 8192 + 64 * d + (unsigned)(hi * (4 * 8192) + r32 * 2)) = (unsigned short)f2bf(o[d][r] * ss[r] * g); } }
.LBB0_1210:
	v_mul_f32_e32 v74, v74, v64
	v_mul_f32_e32 v74, v74, v0
	v_bfe_u32 v76, v74, 16, 1
	s_lshl_b32 s46, s83, 18
	v_add3_u32 v74, v74, v76, s42
	v_lshl_add_u64 v[76:77], v[18:19], 0, s[46:47]
	global_store_short_d16_hi v[76:77], v74, off offset:256
	s_or_b64 exec, exec, s[38:39]
	s_and_saveexec_b64 s[38:39], s[0:1]
	s_cbranch_execz .LBB0_1036
.LBB0_1211:
	v_mul_f32_e32 v74, v75, v65
	v_mul_f32_e32 v74, v74, v0
	v_bfe_u32 v75, v74, 16, 1
	s_lshl_b32 s46, s81, 13
	v_add3_u32 v76, v74, v75, s42
	v_lshl_add_u64 v[74:75], v[18:19], 0, s[46:47]
	global_store_short_d16_hi v[74:75], v76, off offset:256
	s_or_b64 exec, exec, s[38:39]
	s_and_saveexec_b64 s[38:39], s[4:5]
	s_cbranch_execz .LBB0_1037
.LBB0_1212:
	v_mul_f32_e32 v72, v72, v80
	v_mul_f32_e32 v72, v72, v0
	v_bfe_u32 v74, v72, 16, 1
	s_lshl_b32 s46, s44, 13
	v_add3_u32 v72, v72, v74, s42
	v_lshl_add_u64 v[74:75], v[18:19], 0, s[46:47]
	global_store_short_d16_hi v[74:75], v72, off offset:256
	s_or_b64 exec, exec, s[38:39]
	s_and_saveexec_b64 s[38:39], s[6:7]
	s_cbranch_execz .LBB0_1038
.LBB0_1213:
	v_mul_f32_e32 v72, v73, v81
	v_mul_f32_e32 v72, v72, v0
	v_bfe_u32 v73, v72, 16, 1
	s_lshl_b32 s46, s93, 13
	v_add3_u32 v74, v72, v73, s42
	v_lshl_add_u64 v[72:73], v[18:19], 0, s[46:47]
	global_store_short_d16_hi v[72:73], v74, off offset:256
	s_or_b64 exec, exec, s[38:39]
	s_and_saveexec_b64 s[38:39], s[8:9]
	s_cbranch_execz .LBB0_1039
.LBB0_1214:
	v_mul_f32_e32 v70, v70, v138
	v_mul_f32_e32 v70, v70, v0
	v_bfe_u32 v72, v70, 16, 1
	s_lshl_b32 s46, s50, 13
	v_add3_u32 v70, v70, v72, s42
	v_lshl_add_u64 v[72:73], v[18:19], 0, s[46:47]
	global_store_short_d16_hi v[72:73], v70, off offset:256
	s_or_b64 exec, exec, s[38:39]
	s_and_saveexec_b64 s[38:39], s[10:11]
	s_cbranch_execz .LBB0_1040
.LBB0_1215:
	v_mul_f32_e32 v70, v71, v139
	v_mul_f32_e32 v70, v70, v0
	v_bfe_u32 v71, v70, 16, 1
	s_lshl_b32 s46, s58, 13
	v_add3_u32 v72, v70, v71, s42
	v_lshl_add_u64 v[70:71], v[18:19], 0, s[46:47]
	global_store_short_d16_hi v[70:71], v72, off offset:256
	s_or_b64 exec, exec, s[38:39]
	s_and_saveexec_b64 s[38:39], s[12:13]
	s_cbranch_execz .LBB0_1041
.LBB0_1216:
	v_mul_f32_e32 v68, v68, v112
	v_mul_f32_e32 v68, v68, v0
	v_bfe_u32 v70, v68, 16, 1
	s_lshl_b32 s46, s45, 13
	v_add3_u32 v68, v68, v70, s42
	v_lshl_add_u64 v[70:71], v[18:19], 0, s[46:47]
	global_store_short_d16_hi v[70:71], v68, off offset:256
	s_or_b64 exec, exec, s[38:39]
	s_and_saveexec_b64 s[38:39], s[14:15]
	s_cbranch_execz .LBB0_1042
.LBB0_1217:
	v_mul_f32_e32 v68, v69, v113
	v_mul_f32_e32 v68, v68, v0
	v_bfe_u32 v69, v68, 16, 1
	s_lshl_b32 s46, s41, 13
	v_add3_u32 v70, v68, v69, s42
	v_lshl_add_u64 v[68:69], v[18:19], 0, s[46:47]
	global_store_short_d16_hi v[68:69], v70, off offset:256
	s_or_b64 exec, exec, s[38:39]
	s_and_saveexec_b64 s[38:39], s[16:17]
	s_cbranch_execz .LBB0_1043
.LBB0_1218:
	v_mul_f32_e32 v66, v66, v128
	v_mul_f32_e32 v66, v66, v0
	v_bfe_u32 v68, v66, 16, 1
	s_lshl_b32 s46, s59, 13
	v_add3_u32 v66, v66, v68, s42
	v_lshl_add_u64 v[68:69], v[18:19], 0, s[46:47]
	global_store_short_d16_hi v[68:69], v66, off offset:256
	s_or_b64 exec, exec, s[38:39]
	s_and_saveexec_b64 s[38:39], s[18:19]
	s_cbranch_execz .LBB0_1044
.LBB0_1219:
	v_mul_f32_e32 v66, v67, v129
	v_mul_f32_e32 v66, v66, v0
	v_bfe_u32 v67, v66, 16, 1
	s_lshl_b32 s46, s2, 13
	v_add3_u32 v68, v66, v67, s42
	v_lshl_add_u64 v[66:67], v[18:19], 0, s[46:47]
	global_store_short_d16_hi v[66:67], v68, off offset:256
	s_or_b64 exec, exec, s[38:39]
	s_and_saveexec_b64 s[38:39], s[20:21]
	s_cbranch_execz .LBB0_1045
.LBB0_1220:
	v_mul_f32_e32 v56, v56, v140
	v_mul_f32_e32 v56, v56, v0
	v_bfe_u32 v66, v56, 16, 1
	s_lshl_b32 s46, s88, 13
	v_add3_u32 v56, v56, v66, s42
	v_lshl_add_u64 v[66:67], v[18:19], 0, s[46:47]
	global_store_short_d16_hi v[66:67], v56, off offset:256
	s_or_b64 exec, exec, s[38:39]
	s_and_saveexec_b64 s[38:39], s[22:23]
	s_cbranch_execz .LBB0_1046
.LBB0_1221:
	v_mul_f32_e32 v56, v57, v141
	v_mul_f32_e32 v56, v56, v0
	v_bfe_u32 v57, v56, 16, 1
	s_lshl_b32 s46, s89, 13
	v_add3_u32 v66, v56, v57, s42
	v_lshl_add_u64 v[56:57], v[18:19], 0, s[46:47]
	global_store_short_d16_hi v[56:57], v66, off offset:256
	s_or_b64 exec, exec, s[38:39]
	s_and_saveexec_b64 s[38:39], s[24:25]
	s_cbranch_execz .LBB0_1047
.LBB0_1222:
	v_mul_f32_e32 v52, v52, v48
	v_mul_f32_e32 v52, v52, v0
	v_bfe_u32 v56, v52, 16, 1
	s_lshl_b32 s46, s90, 13
	v_add3_u32 v52, v52, v56, s42
	v_lshl_add_u64 v[56:57], v[18:19], 0, s[46:47]
	global_store_short_d16_hi v[56:57], v52, off offset:256
	s_or_b64 exec, exec, s[38:39]
	s_and_saveexec_b64 s[38:39], s[26:27]
	s_cbranch_execz .LBB0_1048
.LBB0_1223:
	v_mul_f32_e32 v52, v53, v49
	v_mul_f32_e32 v52, v52, v0
	v_bfe_u32 v53, v52, 16, 1
	s_lshl_b32 s46, s61, 13
	v_add3_u32 v56, v52, v53, s42
	v_lshl_add_u64 v[52:53], v[18:19], 0, s[46:47]
	global_store_short_d16_hi v[52:53], v56, off offset:256
	s_or_b64 exec, exec, s[38:39]
	s_and_saveexec_b64 s[38:39], s[28:29]
	s_cbranch_execz .LBB0_1049
.LBB0_1224:
	v_mul_f32_e32 v50, v50, v32
	v_mul_f32_e32 v50, v50, v0
	v_bfe_u32 v52, v50, 16, 1
	s_lshl_b32 s46, s60, 13
	v_add3_u32 v50, v50, v52, s42
	v_lshl_add_u64 v[52:53], v[18:19], 0, s[46:47]
	global_store_short_d16_hi v[52:53], v50, off offset:256
	s_or_b64 exec, exec, s[38:39]
	s_and_saveexec_b64 s[38:39], s[30:31]
	s_cbranch_execz .LBB0_1050
.LBB0_1225:
	v_mul_f32_e32 v50, v51, v33
	v_mul_f32_e32 v0, v50, v0
	v_bfe_u32 v50, v0, 16, 1
	s_lshl_b32 s46, s80, 13
	v_add3_u32 v0, v0, v50, s42
	v_lshl_add_u64 v[50:51], v[18:19], 0, s[46:47]
	global_store_short_d16_hi v[50:51], v0, off offset:256
	s_or_b64 exec, exec, s[38:39]
	v_mov_b32_e32 v0, v244
	s_and_saveexec_b64 s[38:39], vcc
	s_cbranch_execz .LBB0_1051
; __device__ __forceinline__ unsigned f2bf(float f) { unsigned u = __builtin_bit_cast(unsigned, f); return (u + 0x7fffu + ((u >> 16) & 1u)) >> 16; }
; __device__ __forceinline__ void dattn_unit(const bf16* __restrict__ Qb, const bf16* __restrict__ Kh, const bf16* __restrict__ Vh, int nq, int kv_lo, int kv_hi, int NT, ...
;     ...
;     for (int d = 0; d < 8; ++d) { const float g = gnorm[32 * d + r32];
; #pragma unroll
;       for (int r = 0; r < 16; ++r) { const int rk = rg * 32 + (r & 3) + 8 * (r >> 2);
;           if (rk + 4 * hi < nq) *(unsigned short*)((unsigned char*)outp + (size_t)rk * 8192 + 64 * d + (unsigned)(hi * (4 * 8192) + r32 * 2)) = (unsigned short)f2bf(o[d][r] * ss[r] * g); } }
.LBB0_1226:
	v_mul_f32_e32 v50, v54, v64
	v_mul_f32_e32 v50, v50, v0
	v_bfe_u32 v51, v50, 16, 1
	s_lshl_b32 s46, s83, 18
	v_add3_u32 v52, v50, v51, s42
	v_lshl_add_u64 v[50:51], v[18:19], 0, s[46:47]
	global_store_short_d16_hi v[50:51], v52, off offset:320
	s_or_b64 exec, exec, s[38:39]
	s_and_saveexec_b64 s[38:39], s[0:1]
	s_cbranch_execz .LBB0_1052
.LBB0_1227:
	v_mul_f32_e32 v50, v55, v65
	v_mul_f32_e32 v50, v50, v0
	v_bfe_u32 v51, v50, 16, 1
	s_lshl_b32 s46, s81, 13
	v_add3_u32 v52, v50, v51, s42
	v_lshl_add_u64 v[50:51], v[18:19], 0, s[46:47]
	global_store_short_d16_hi v[50:51], v52, off offset:320
	s_or_b64 exec, exec, s[38:39]
	s_and_saveexec_b64 s[38:39], s[4:5]
	s_cbranch_execz .LBB0_1053
.LBB0_1228:
	v_mul_f32_e32 v50, v58, v80
	v_mul_f32_e32 v50, v50, v0
	v_bfe_u32 v51, v50, 16, 1
	s_lshl_b32 s46, s44, 13
	v_add3_u32 v52, v50, v51, s42
	v_lshl_add_u64 v[50:51], v[18:19], 0, s[46:47]
	global_store_short_d16_hi v[50:51], v52, off offset:320
	s_or_b64 exec, exec, s[38:39]
	s_and_saveexec_b64 s[38:39], s[6:7]
	s_cbranch_execz .LBB0_1054
.LBB0_1229:
	v_mul_f32_e32 v50, v59, v81
	v_mul_f32_e32 v50, v50, v0
	v_bfe_u32 v51, v50, 16, 1
	s_lshl_b32 s46, s93, 13
	v_add3_u32 v52, v50, v51, s42
	v_lshl_add_u64 v[50:51], v[18:19], 0, s[46:47]
	global_store_short_d16_hi v[50:51], v52, off offset:320
	s_or_b64 exec, exec, s[38:39]
	s_and_saveexec_b64 s[38:39], s[8:9]
	s_cbranch_execz .LBB0_1055
.LBB0_1230:
	v_mul_f32_e32 v50, v60, v138
	v_mul_f32_e32 v50, v50, v0
	v_bfe_u32 v51, v50, 16, 1
	s_lshl_b32 s46, s50, 13
	v_add3_u32 v52, v50, v51, s42
	v_lshl_add_u64 v[50:51], v[18:19], 0, s[46:47]
	global_store_short_d16_hi v[50:51], v52, off offset:320
	s_or_b64 exec, exec, s[38:39]
	s_and_saveexec_b64 s[38:39], s[10:11]
	s_cbranch_execz .LBB0_1056
.LBB0_1231:
	v_mul_f32_e32 v50, v61, v139
	v_mul_f32_e32 v50, v50, v0
	v_bfe_u32 v51, v50, 16, 1
	s_lshl_b32 s46, s58, 13
	v_add3_u32 v52, v50, v51, s42
	v_lshl_add_u64 v[50:51], v[18:19], 0, s[46:47]
	global_store_short_d16_hi v[50:51], v52, off offset:320
	s_or_b64 exec, exec, s[38:39]
	s_and_saveexec_b64 s[38:39], s[12:13]
	s_cbranch_execz .LBB0_1057
.LBB0_1232:
	v_mul_f32_e32 v40, v40, v112
	v_mul_f32_e32 v40, v40, v0
	v_bfe_u32 v50, v40, 16, 1
	s_lshl_b32 s46, s45, 13
	v_add3_u32 v40, v40, v50, s42
	v_lshl_add_u64 v[50:51], v[18:19], 0, s[46:47]
	global_store_short_d16_hi v[50:51], v40, off offset:320
	s_or_b64 exec, exec, s[38:39]
	s_and_saveexec_b64 s[38:39], s[14:15]
	s_cbranch_execz .LBB0_1058
.LBB0_1233:
	v_mul_f32_e32 v40, v41, v113
	v_mul_f32_e32 v40, v40, v0
	v_bfe_u32 v41, v40, 16, 1
	s_lshl_b32 s46, s41, 13
	v_add3_u32 v50, v40, v41, s42
	v_lshl_add_u64 v[40:41], v[18:19], 0, s[46:47]
	global_store_short_d16_hi v[40:41], v50, off offset:320
	s_or_b64 exec, exec, s[38:39]
	s_and_saveexec_b64 s[38:39], s[16:17]
	s_cbranch_execz .LBB0_1059
.LBB0_1234:
	v_mul_f32_e32 v40, v42, v128
	v_mul_f32_e32 v40, v40, v0
	v_bfe_u32 v41, v40, 16, 1
	s_lshl_b32 s46, s59, 13
	v_add3_u32 v42, v40, v41, s42
	v_lshl_add_u64 v[40:41], v[18:19], 0, s[46:47]
	global_store_short_d16_hi v[40:41], v42, off offset:320
	s_or_b64 exec, exec, s[38:39]
	s_and_saveexec_b64 s[38:39], s[18:19]
	s_cbranch_execz .LBB0_1060
.LBB0_1235:
	v_mul_f32_e32 v40, v43, v129
	v_mul_f32_e32 v40, v40, v0
	v_bfe_u32 v41, v40, 16, 1
	s_lshl_b32 s46, s2, 13
	v_add3_u32 v42, v40, v41, s42
	v_lshl_add_u64 v[40:41], v[18:19], 0, s[46:47]
	global_store_short_d16_hi v[40:41], v42, off offset:320
	s_or_b64 exec, exec, s[38:39]
	s_and_saveexec_b64 s[38:39], s[20:21]
	s_cbranch_execz .LBB0_1061
.LBB0_1236:
	v_mul_f32_e32 v40, v62, v140
	v_mul_f32_e32 v40, v40, v0
	v_bfe_u32 v41, v40, 16, 1
	s_lshl_b32 s46, s88, 13
	v_add3_u32 v42, v40, v41, s42
	v_lshl_add_u64 v[40:41], v[18:19], 0, s[46:47]
	global_store_short_d16_hi v[40:41], v42, off offset:320
	s_or_b64 exec, exec, s[38:39]
	s_and_saveexec_b64 s[38:39], s[22:23]
	s_cbranch_execz .LBB0_1062
.LBB0_1237:
	v_mul_f32_e32 v40, v63, v141
	v_mul_f32_e32 v40, v40, v0
	v_bfe_u32 v41, v40, 16, 1
	s_lshl_b32 s46, s89, 13
	v_add3_u32 v42, v40, v41, s42
	v_lshl_add_u64 v[40:41], v[18:19], 0, s[46:47]
	global_store_short_d16_hi v[40:41], v42, off offset:320
	s_or_b64 exec, exec, s[38:39]
	s_and_saveexec_b64 s[38:39], s[24:25]
	s_cbranch_execz .LBB0_1063
.LBB0_1238:
	v_mul_f32_e32 v40, v46, v48
	v_mul_f32_e32 v40, v40, v0
	v_bfe_u32 v41, v40, 16, 1
	s_lshl_b32 s46, s90, 13
	v_add3_u32 v42, v40, v41, s42
	v_lshl_add_u64 v[40:41], v[18:19], 0, s[46:47]
	global_store_short_d16_hi v[40:41], v42, off offset:320
	s_or_b64 exec, exec, s[38:39]
	s_and_saveexec_b64 s[38:39], s[26:27]
	s_cbranch_execz .LBB0_1064
.LBB0_1239:
	v_mul_f32_e32 v40, v47, v49
	v_mul_f32_e32 v40, v40, v0
	v_bfe_u32 v41, v40, 16, 1
	s_lshl_b32 s46, s61, 13
	v_add3_u32 v42, v40, v41, s42
	v_lshl_add_u64 v[40:41], v[18:19], 0, s[46:47]
	global_store_short_d16_hi v[40:41], v42, off offset:320
	s_or_b64 exec, exec, s[38:39]
	s_and_saveexec_b64 s[38:39], s[28:29]
	s_cbranch_execz .LBB0_1065
.LBB0_1240:
	v_mul_f32_e32 v40, v44, v32
	v_mul_f32_e32 v40, v40, v0
	v_bfe_u32 v41, v40, 16, 1
	s_lshl_b32 s46, s60, 13
	v_add3_u32 v42, v40, v41, s42
	v_lshl_add_u64 v[40:41], v[18:19], 0, s[46:47]
	global_store_short_d16_hi v[40:41], v42, off offset:320
	s_or_b64 exec, exec, s[38:39]
	s_and_saveexec_b64 s[38:39], s[30:31]
	s_cbranch_execz .LBB0_1066
.LBB0_1241:
	v_mul_f32_e32 v40, v45, v33
	v_mul_f32_e32 v0, v40, v0
	v_bfe_u32 v40, v0, 16, 1
	s_lshl_b32 s46, s80, 13
	v_add3_u32 v0, v0, v40, s42
	v_lshl_add_u64 v[40:41], v[18:19], 0, s[46:47]
	global_store_short_d16_hi v[40:41], v0, off offset:320
	s_or_b64 exec, exec, s[38:39]
	v_mov_b32_e32 v0, v245
	s_and_saveexec_b64 s[38:39], vcc
	s_cbranch_execz .LBB0_1067
; __device__ __forceinline__ unsigned f2bf(float f) { unsigned u = __builtin_bit_cast(unsigned, f); return (u + 0x7fffu + ((u >> 16) & 1u)) >> 16; }
; __device__ __forceinline__ void dattn_unit(const bf16* __restrict__ Qb, const bf16* __restrict__ Kh, const bf16* __restrict__ Vh, int nq, int kv_lo, int kv_hi, int NT, ...
;     ...
;     for (int d = 0; d < 8; ++d) { const float g = gnorm[32 * d + r32];
; #pragma unroll
;       for (int r = 0; r < 16; ++r) { const int rk = rg * 32 + (r & 3) + 8 * (r >> 2);
;           if (rk + 4 * hi < nq) *(unsigned short*)((unsigned char*)outp + (size_t)rk * 8192 + 64 * d + (unsigned)(hi * (4 * 8192) + r32 * 2)) = (unsigned short)f2bf(o[d][r] * ss[r] * g); } }
.LBB0_1242:
	v_mul_f32_e32 v34, v34, v64
	v_mul_f32_e32 v34, v34, v0
	v_bfe_u32 v40, v34, 16, 1
	s_lshl_b32 s46, s83, 18
	v_add3_u32 v34, v34, v40, s42
	v_lshl_add_u64 v[40:41], v[18:19], 0, s[46:47]
	global_store_short_d16_hi v[40:41], v34, off offset:384
	s_or_b64 exec, exec, s[38:39]
	s_and_saveexec_b64 s[38:39], s[0:1]
	s_cbranch_execz .LBB0_1068
.LBB0_1243:
	v_mul_f32_e32 v34, v35, v65
	v_mul_f32_e32 v34, v34, v0
	v_bfe_u32 v35, v34, 16, 1
	s_lshl_b32 s46, s81, 13
	v_add3_u32 v40, v34, v35, s42
	v_lshl_add_u64 v[34:35], v[18:19], 0, s[46:47]
	global_store_short_d16_hi v[34:35], v40, off offset:384
	s_or_b64 exec, exec, s[38:39]
	s_and_saveexec_b64 s[38:39], s[4:5]
	s_cbranch_execz .LBB0_1069
.LBB0_1244:
	v_mul_f32_e32 v34, v36, v80
	v_mul_f32_e32 v34, v34, v0
	v_bfe_u32 v35, v34, 16, 1
	s_lshl_b32 s46, s44, 13
	v_add3_u32 v36, v34, v35, s42
	v_lshl_add_u64 v[34:35], v[18:19], 0, s[46:47]
	global_store_short_d16_hi v[34:35], v36, off offset:384
	s_or_b64 exec, exec, s[38:39]
	s_and_saveexec_b64 s[38:39], s[6:7]
	s_cbranch_execz .LBB0_1070
.LBB0_1245:
	v_mul_f32_e32 v34, v37, v81
	v_mul_f32_e32 v34, v34, v0
	v_bfe_u32 v35, v34, 16, 1
	s_lshl_b32 s46, s93, 13
	v_add3_u32 v36, v34, v35, s42
	v_lshl_add_u64 v[34:35], v[18:19], 0, s[46:47]
	global_store_short_d16_hi v[34:35], v36, off offset:384
	s_or_b64 exec, exec, s[38:39]
	s_and_saveexec_b64 s[38:39], s[8:9]
	s_cbranch_execz .LBB0_1071
.LBB0_1246:
	v_mul_f32_e32 v22, v22, v138
	v_mul_f32_e32 v22, v22, v0
	v_bfe_u32 v34, v22, 16, 1
	s_lshl_b32 s46, s50, 13
	v_add3_u32 v22, v22, v34, s42
	v_lshl_add_u64 v[34:35], v[18:19], 0, s[46:47]
	global_store_short_d16_hi v[34:35], v22, off offset:384
	s_or_b64 exec, exec, s[38:39]
	s_and_saveexec_b64 s[38:39], s[10:11]
	s_cbranch_execz .LBB0_1072
.LBB0_1247:
	v_mul_f32_e32 v22, v23, v139
	v_mul_f32_e32 v22, v22, v0
	v_bfe_u32 v23, v22, 16, 1
	s_lshl_b32 s46, s58, 13
	v_add3_u32 v34, v22, v23, s42
	v_lshl_add_u64 v[22:23], v[18:19], 0, s[46:47]
	global_store_short_d16_hi v[22:23], v34, off offset:384
	s_or_b64 exec, exec, s[38:39]
	s_and_saveexec_b64 s[38:39], s[12:13]
	s_cbranch_execz .LBB0_1073
.LBB0_1248:
	v_mul_f32_e32 v22, v24, v112
	v_mul_f32_e32 v22, v22, v0
	v_bfe_u32 v23, v22, 16, 1
	s_lshl_b32 s46, s45, 13
	v_add3_u32 v24, v22, v23, s42
	v_lshl_add_u64 v[22:23], v[18:19], 0, s[46:47]
	global_store_short_d16_hi v[22:23], v24, off offset:384
	s_or_b64 exec, exec, s[38:39]
	s_and_saveexec_b64 s[38:39], s[14:15]
	s_cbranch_execz .LBB0_1074
.LBB0_1249:
	v_mul_f32_e32 v22, v25, v113
	v_mul_f32_e32 v22, v22, v0
	v_bfe_u32 v23, v22, 16, 1
	s_lshl_b32 s46, s41, 13
	v_add3_u32 v24, v22, v23, s42
	v_lshl_add_u64 v[22:23], v[18:19], 0, s[46:47]
	global_store_short_d16_hi v[22:23], v24, off offset:384
	s_or_b64 exec, exec, s[38:39]
	s_and_saveexec_b64 s[38:39], s[16:17]
	s_cbranch_execz .LBB0_1075
.LBB0_1250:
	v_mul_f32_e32 v22, v26, v128
	v_mul_f32_e32 v22, v22, v0
	v_bfe_u32 v23, v22, 16, 1
	s_lshl_b32 s46, s59, 13
	v_add3_u32 v24, v22, v23, s42
	v_lshl_add_u64 v[22:23], v[18:19], 0, s[46:47]
	global_store_short_d16_hi v[22:23], v24, off offset:384
	s_or_b64 exec, exec, s[38:39]
	s_and_saveexec_b64 s[38:39], s[18:19]
	s_cbranch_execz .LBB0_1076
.LBB0_1251:
	v_mul_f32_e32 v22, v27, v129
	v_mul_f32_e32 v22, v22, v0
	v_bfe_u32 v23, v22, 16, 1
	s_lshl_b32 s46, s2, 13
	v_add3_u32 v24, v22, v23, s42
	v_lshl_add_u64 v[22:23], v[18:19], 0, s[46:47]
	global_store_short_d16_hi v[22:23], v24, off offset:384
	s_or_b64 exec, exec, s[38:39]
	s_and_saveexec_b64 s[38:39], s[20:21]
	s_cbranch_execz .LBB0_1077
.LBB0_1252:
	v_mul_f32_e32 v22, v38, v140
	v_mul_f32_e32 v22, v22, v0
	v_bfe_u32 v23, v22, 16, 1
	s_lshl_b32 s46, s88, 13
	v_add3_u32 v24, v22, v23, s42
	v_lshl_add_u64 v[22:23], v[18:19], 0, s[46:47]
	global_store_short_d16_hi v[22:23], v24, off offset:384
	s_or_b64 exec, exec, s[38:39]
	s_and_saveexec_b64 s[38:39], s[22:23]
	s_cbranch_execz .LBB0_1078
.LBB0_1253:
	v_mul_f32_e32 v22, v39, v141
	v_mul_f32_e32 v22, v22, v0
	v_bfe_u32 v23, v22, 16, 1
	s_lshl_b32 s46, s89, 13
	v_add3_u32 v24, v22, v23, s42
	v_lshl_add_u64 v[22:23], v[18:19], 0, s[46:47]
	global_store_short_d16_hi v[22:23], v24, off offset:384
	s_or_b64 exec, exec, s[38:39]
	s_and_saveexec_b64 s[38:39], s[24:25]
	s_cbranch_execz .LBB0_1079
.LBB0_1254:
	v_mul_f32_e32 v22, v30, v48
	v_mul_f32_e32 v22, v22, v0
	v_bfe_u32 v23, v22, 16, 1
	s_lshl_b32 s46, s90, 13
	v_add3_u32 v24, v22, v23, s42
	v_lshl_add_u64 v[22:23], v[18:19], 0, s[46:47]
	global_store_short_d16_hi v[22:23], v24, off offset:384
	s_or_b64 exec, exec, s[38:39]
	s_and_saveexec_b64 s[38:39], s[26:27]
	s_cbranch_execz .LBB0_1080
.LBB0_1255:
	v_mul_f32_e32 v22, v31, v49
	v_mul_f32_e32 v22, v22, v0
	v_bfe_u32 v23, v22, 16, 1
	s_lshl_b32 s46, s61, 13
	v_add3_u32 v24, v22, v23, s42
	v_lshl_add_u64 v[22:23], v[18:19], 0, s[46:47]
	global_store_short_d16_hi v[22:23], v24, off offset:384
	s_or_b64 exec, exec, s[38:39]
	s_and_saveexec_b64 s[38:39], s[28:29]
	s_cbranch_execz .LBB0_1081
.LBB0_1256:
	v_mul_f32_e32 v22, v28, v32
	v_mul_f32_e32 v22, v22, v0
	v_bfe_u32 v23, v22, 16, 1
	s_lshl_b32 s46, s60, 13
	v_add3_u32 v24, v22, v23, s42
	v_lshl_add_u64 v[22:23], v[18:19], 0, s[46:47]
	global_store_short_d16_hi v[22:23], v24, off offset:384
	s_or_b64 exec, exec, s[38:39]
	s_and_saveexec_b64 s[38:39], s[30:31]
	s_cbranch_execz .LBB0_1082
; __device__ __forceinline__ unsigned f2bf(float f) { unsigned u = __builtin_bit_cast(unsigned, f); return (u + 0x7fffu + ((u >> 16) & 1u)) >> 16; }
; __device__ __forceinline__ void dattn_unit(const bf16* __restrict__ Qb, const bf16* __restrict__ Kh, const bf16* __restrict__ Vh, int nq, int kv_lo, int kv_hi, int NT, ...
;     ...
;     for (int d = 0; d < 8; ++d) { const float g = gnorm[32 * d + r32];
; #pragma unroll
;       for (int r = 0; r < 16; ++r) { const int rk = rg * 32 + (r & 3) + 8 * (r >> 2);
;           if (rk + 4 * hi < nq) *(unsigned short*)((unsigned char*)outp + (size_t)rk * 8192 + 64 * d + (unsigned)(hi * (4 * 8192) + r32 * 2)) = (unsigned short)f2bf(o[d][r] * ss[r] * g); } }
.LBB0_1257:
	v_mul_f32_e32 v22, v29, v33
	v_mul_f32_e32 v0, v22, v0
	v_bfe_u32 v22, v0, 16, 1
	s_lshl_b32 s46, s80, 13
	v_add3_u32 v0, v0, v22, s42
	v_lshl_add_u64 v[22:23], v[18:19], 0, s[46:47]
	global_store_short_d16_hi v[22:23], v0, off offset:384
	s_or_b64 exec, exec, s[38:39]
	v_mov_b32_e32 v0, v246
	s_and_saveexec_b64 s[38:39], vcc
	s_cbranch_execz .LBB0_1083
.LBB0_1258:
	v_mul_f32_e32 v2, v2, v64
	v_mul_f32_e32 v2, v2, v0
	v_bfe_u32 v16, v2, 16, 1
	s_lshl_b32 s46, s83, 18
	v_add3_u32 v2, v2, v16, s42
	v_lshl_add_u64 v[16:17], v[18:19], 0, s[46:47]
	global_store_short_d16_hi v[16:17], v2, off offset:448
	s_or_b64 exec, exec, s[38:39]
	s_and_saveexec_b64 s[38:39], s[0:1]
	s_cbranch_execz .LBB0_1084
.LBB0_1259:
	v_mul_f32_e32 v2, v3, v65
	v_mul_f32_e32 v2, v2, v0
	v_bfe_u32 v3, v2, 16, 1
	s_lshl_b32 s46, s81, 13
	v_add3_u32 v16, v2, v3, s42
	v_lshl_add_u64 v[2:3], v[18:19], 0, s[46:47]
	global_store_short_d16_hi v[2:3], v16, off offset:448
	s_or_b64 exec, exec, s[38:39]
	s_and_saveexec_b64 s[0:1], s[4:5]
	s_cbranch_execz .LBB0_1085
.LBB0_1260:
	v_mul_f32_e32 v2, v4, v80
	v_mul_f32_e32 v2, v2, v0
	v_bfe_u32 v3, v2, 16, 1
	s_lshl_b32 s46, s44, 13
	v_add3_u32 v4, v2, v3, s42
	v_lshl_add_u64 v[2:3], v[18:19], 0, s[46:47]
	global_store_short_d16_hi v[2:3], v4, off offset:448
	s_or_b64 exec, exec, s[0:1]
	s_and_saveexec_b64 s[0:1], s[6:7]
	s_cbranch_execz .LBB0_1086
.LBB0_1261:
	v_mul_f32_e32 v2, v5, v81
	v_mul_f32_e32 v2, v2, v0
	v_bfe_u32 v3, v2, 16, 1
	s_lshl_b32 s46, s93, 13
	v_add3_u32 v4, v2, v3, s42
	v_lshl_add_u64 v[2:3], v[18:19], 0, s[46:47]
	global_store_short_d16_hi v[2:3], v4, off offset:448
	s_or_b64 exec, exec, s[0:1]
	s_and_saveexec_b64 s[0:1], s[8:9]
	s_cbranch_execz .LBB0_1087
.LBB0_1262:
	v_mul_f32_e32 v2, v6, v138
	v_mul_f32_e32 v2, v2, v0
	v_bfe_u32 v3, v2, 16, 1
	s_lshl_b32 s46, s50, 13
	v_add3_u32 v4, v2, v3, s42
	v_lshl_add_u64 v[2:3], v[18:19], 0, s[46:47]
	global_store_short_d16_hi v[2:3], v4, off offset:448
	s_or_b64 exec, exec, s[0:1]
	s_and_saveexec_b64 s[0:1], s[10:11]
	s_cbranch_execz .LBB0_1088
.LBB0_1263:
	v_mul_f32_e32 v2, v7, v139
	v_mul_f32_e32 v2, v2, v0
	v_bfe_u32 v3, v2, 16, 1
	s_lshl_b32 s46, s58, 13
	v_add3_u32 v4, v2, v3, s42
	v_lshl_add_u64 v[2:3], v[18:19], 0, s[46:47]
	global_store_short_d16_hi v[2:3], v4, off offset:448
	s_or_b64 exec, exec, s[0:1]
	s_and_saveexec_b64 s[0:1], s[12:13]
	s_cbranch_execz .LBB0_1089
.LBB0_1264:
	v_mul_f32_e32 v2, v8, v112
	v_mul_f32_e32 v2, v2, v0
	v_bfe_u32 v3, v2, 16, 1
	s_lshl_b32 s46, s45, 13
	v_add3_u32 v4, v2, v3, s42
	v_lshl_add_u64 v[2:3], v[18:19], 0, s[46:47]
	global_store_short_d16_hi v[2:3], v4, off offset:448
	s_or_b64 exec, exec, s[0:1]
	s_and_saveexec_b64 s[0:1], s[14:15]
	s_cbranch_execz .LBB0_1090
.LBB0_1265:
	v_mul_f32_e32 v2, v9, v113
	v_mul_f32_e32 v2, v2, v0
	v_bfe_u32 v3, v2, 16, 1
	s_lshl_b32 s46, s41, 13
	v_add3_u32 v4, v2, v3, s42
	v_lshl_add_u64 v[2:3], v[18:19], 0, s[46:47]
	global_store_short_d16_hi v[2:3], v4, off offset:448
	s_or_b64 exec, exec, s[0:1]
	s_and_saveexec_b64 s[0:1], s[16:17]
	s_cbranch_execz .LBB0_1091
.LBB0_1266:
	v_mul_f32_e32 v2, v10, v128
	v_mul_f32_e32 v2, v2, v0
	v_bfe_u32 v3, v2, 16, 1
	s_lshl_b32 s46, s59, 13
	v_add3_u32 v4, v2, v3, s42
	v_lshl_add_u64 v[2:3], v[18:19], 0, s[46:47]
	global_store_short_d16_hi v[2:3], v4, off offset:448
	s_or_b64 exec, exec, s[0:1]
	s_and_saveexec_b64 s[0:1], s[18:19]
	s_cbranch_execz .LBB0_1092
.LBB0_1267:
	v_mul_f32_e32 v2, v11, v129
	v_mul_f32_e32 v2, v2, v0
	v_bfe_u32 v3, v2, 16, 1
	s_lshl_b32 s46, s2, 13
	v_add3_u32 v4, v2, v3, s42
	v_lshl_add_u64 v[2:3], v[18:19], 0, s[46:47]
	global_store_short_d16_hi v[2:3], v4, off offset:448
	s_or_b64 exec, exec, s[0:1]
	s_and_saveexec_b64 s[0:1], s[20:21]
	s_cbranch_execz .LBB0_1093
.LBB0_1268:
	v_mul_f32_e32 v2, v20, v140
	v_mul_f32_e32 v2, v2, v0
	v_bfe_u32 v3, v2, 16, 1
	s_lshl_b32 s46, s88, 13
	v_add3_u32 v4, v2, v3, s42
	v_lshl_add_u64 v[2:3], v[18:19], 0, s[46:47]
	global_store_short_d16_hi v[2:3], v4, off offset:448
	s_or_b64 exec, exec, s[0:1]
	s_and_saveexec_b64 s[0:1], s[22:23]
	s_cbranch_execz .LBB0_1094
.LBB0_1269:
	v_mul_f32_e32 v2, v21, v141
	v_mul_f32_e32 v2, v2, v0
	v_bfe_u32 v3, v2, 16, 1
	s_lshl_b32 s46, s89, 13
	v_add3_u32 v4, v2, v3, s42
	v_lshl_add_u64 v[2:3], v[18:19], 0, s[46:47]
	global_store_short_d16_hi v[2:3], v4, off offset:448
	s_or_b64 exec, exec, s[0:1]
	s_and_saveexec_b64 s[0:1], s[24:25]
	s_cbranch_execz .LBB0_1095
.LBB0_1270:
	v_mul_f32_e32 v2, v14, v48
	v_mul_f32_e32 v2, v2, v0
	v_bfe_u32 v3, v2, 16, 1
	s_lshl_b32 s46, s90, 13
	v_add3_u32 v4, v2, v3, s42
	v_lshl_add_u64 v[2:3], v[18:19], 0, s[46:47]
	global_store_short_d16_hi v[2:3], v4, off offset:448
	s_or_b64 exec, exec, s[0:1]
	s_and_saveexec_b64 s[0:1], s[26:27]
	s_cbranch_execz .LBB0_1096
.LBB0_1271:
	v_mul_f32_e32 v2, v15, v49
	v_mul_f32_e32 v2, v2, v0
	v_bfe_u32 v3, v2, 16, 1
	s_lshl_b32 s46, s61, 13
	v_add3_u32 v4, v2, v3, s42
	v_lshl_add_u64 v[2:3], v[18:19], 0, s[46:47]
	global_store_short_d16_hi v[2:3], v4, off offset:448
	s_or_b64 exec, exec, s[0:1]
	s_and_saveexec_b64 s[0:1], s[28:29]
	s_cbranch_execz .LBB0_1097
.LBB0_1272:
	v_mul_f32_e32 v2, v12, v32
	v_mul_f32_e32 v2, v2, v0
	v_bfe_u32 v3, v2, 16, 1
	s_lshl_b32 s46, s60, 13
	v_add3_u32 v4, v2, v3, s42
	v_lshl_add_u64 v[2:3], v[18:19], 0, s[46:47]
	global_store_short_d16_hi v[2:3], v4, off offset:448
	s_or_b64 exec, exec, s[0:1]
	s_and_saveexec_b64 s[0:1], s[30:31]
	s_cbranch_execnz .LBB0_1098
	s_branch .LBB0_1099
